# accumulator zeroing removed: first K-loop iteration peeled, first MFMA of each accumulator takes inline 0 as SrcC (all 7 GEMM loops)
# speedup vs baseline: 1.0077x; 1.0022x over previous
.LBB0_243:
	s_lshl_b32 s24, s12, 20
	s_and_b32 s24, s24, 0xff00000
	v_readlane_b32 s36, v248, 22
	v_readlane_b32 s37, v248, 23
	s_add_u32 s24, s36, s24
	s_addc_u32 s35, s37, 0
	s_lshr_b32 s36, s12, 13
	s_and_b32 s36, s36, 0x7ff80
	s_add_u32 s54, s24, s36
	s_addc_u32 s55, s35, 0
	s_lshl_b32 s24, s12, 12
	s_and_b32 s24, s24, 0xff00000
	v_readlane_b32 s38, v248, 24
	v_readlane_b32 s39, v248, 25
	s_add_u32 s24, s38, s24
	s_addc_u32 s35, s39, 0
	s_add_u32 s70, s24, s36
	s_addc_u32 s71, s35, 0
	s_cmp_lt_i32 s1, 1
	v_cmp_gt_i64_e64 s[72:73], s[12:13], -1
	s_cbranch_scc1 .LBB0_253
	s_and_b64 s[12:13], s[72:73], exec
	s_cselect_b32 s24, s55, s5
	s_cselect_b32 s35, s54, s4
	s_cselect_b32 s36, s71, s3
	s_cselect_b32 s37, s70, s2
	s_add_i32 s38, s1, -2
	s_add_u32 s4, s4, 0x80080
	s_addc_u32 s5, s5, 0
	s_add_u32 s39, s2, 0x100
	s_addc_u32 s40, s3, 0
	s_mov_b32 s2, 0
	v_add_u32_e32 v138, s29, v183
	ds_read_b128 v[144:147], v138
	ds_read_b128 v[148:151], v138 offset:1024
	ds_read_b128 v[152:155], v138 offset:2048
	ds_read_b128 v[156:159], v138 offset:3072
	v_add_u32_e32 v138, s34, v183
	ds_read_b128 v[160:163], v138
	ds_read_b128 v[164:167], v138 offset:1024
	ds_read_b128 v[186:189], v138 offset:2048
	ds_read_b128 v[190:193], v138 offset:3072
	s_add_i32 s41, s2, 2
	s_add_u32 s3, s4, 0xfff80080
	s_addc_u32 s12, s5, -1
	s_cmp_eq_u32 s38, s2
	s_cselect_b32 s2, s37, s39
	s_cselect_b32 s13, s24, s12
	s_cselect_b32 s12, s35, s3
	s_cselect_b32 s3, s36, s40
	v_lshl_add_u64 v[228:229], s[4:5], 0, v[140:141]
	s_add_i32 m0, s17, 0xc000
	ds_read_b128 v[194:197], v185
	ds_read_b128 v[198:201], v185 offset:1024
	ds_read_b128 v[202:205], v185 offset:2048
	ds_read_b128 v[208:211], v185 offset:3072
	ds_read_b128 v[212:215], v185 offset:4096
	ds_read_b128 v[216:219], v185 offset:5120
	ds_read_b128 v[220:223], v185 offset:6144
	ds_read_b128 v[224:227], v185 offset:7168
	global_load_lds_dwordx4 v[228:229], off
	v_lshl_add_u64 v[228:229], s[4:5], 0, v[142:143]
	s_add_i32 m0, s17, 0xe000
	s_nop 0
	global_load_lds_dwordx4 v[228:229], off
	s_waitcnt vmcnt(8)
	s_waitcnt lgkmcnt(0)
	s_barrier
	s_setprio 1
	s_waitcnt lgkmcnt(0)
	v_mfma_i32_16x16x64_i8 v[126:129], v[144:147], v[194:197], 0
	v_mfma_i32_16x16x64_i8 v[122:125], v[152:155], v[194:197], 0
	v_mfma_i32_16x16x64_i8 v[118:121], v[144:147], v[202:205], 0
	v_mfma_i32_16x16x64_i8 v[114:117], v[152:155], v[202:205], 0
	v_mfma_i32_16x16x64_i8 v[110:113], v[144:147], v[212:215], 0
	v_mfma_i32_16x16x64_i8 v[106:109], v[152:155], v[212:215], 0
	v_mfma_i32_16x16x64_i8 v[102:105], v[144:147], v[220:223], 0
	v_mfma_i32_16x16x64_i8 v[98:101], v[152:155], v[220:223], 0
	v_mfma_i32_16x16x64_i8 v[126:129], v[148:151], v[198:201], v[126:129]
	v_mfma_i32_16x16x64_i8 v[122:125], v[156:159], v[198:201], v[122:125]
	v_mfma_i32_16x16x64_i8 v[118:121], v[148:151], v[208:211], v[118:121]
	v_mfma_i32_16x16x64_i8 v[114:117], v[156:159], v[208:211], v[114:117]
	v_mfma_i32_16x16x64_i8 v[110:113], v[148:151], v[216:219], v[110:113]
	v_mfma_i32_16x16x64_i8 v[106:109], v[156:159], v[216:219], v[106:109]
	v_mfma_i32_16x16x64_i8 v[102:105], v[148:151], v[224:227], v[102:105]
	v_mfma_i32_16x16x64_i8 v[98:101], v[156:159], v[224:227], v[98:101]
	s_setprio 0
	s_setprio 1
	v_mfma_i32_16x16x64_i8 v[94:97], v[160:163], v[194:197], 0
	v_mfma_i32_16x16x64_i8 v[90:93], v[186:189], v[194:197], 0
	v_mfma_i32_16x16x64_i8 v[86:89], v[160:163], v[202:205], 0
	v_mfma_i32_16x16x64_i8 v[82:85], v[186:189], v[202:205], 0
	v_mfma_i32_16x16x64_i8 v[78:81], v[160:163], v[212:215], 0
	v_mfma_i32_16x16x64_i8 v[74:77], v[186:189], v[212:215], 0
	v_mfma_i32_16x16x64_i8 v[70:73], v[160:163], v[220:223], 0
	v_mfma_i32_16x16x64_i8 v[66:69], v[186:189], v[220:223], 0
	v_mfma_i32_16x16x64_i8 v[94:97], v[164:167], v[198:201], v[94:97]
	v_mfma_i32_16x16x64_i8 v[90:93], v[190:193], v[198:201], v[90:93]
	v_mfma_i32_16x16x64_i8 v[86:89], v[164:167], v[208:211], v[86:89]
	v_mfma_i32_16x16x64_i8 v[82:85], v[190:193], v[208:211], v[82:85]
	v_mfma_i32_16x16x64_i8 v[78:81], v[164:167], v[216:219], v[78:81]
	v_mfma_i32_16x16x64_i8 v[74:77], v[190:193], v[216:219], v[74:77]
	v_mfma_i32_16x16x64_i8 v[70:73], v[164:167], v[224:227], v[70:73]
	v_mfma_i32_16x16x64_i8 v[66:69], v[190:193], v[224:227], v[66:69]
	s_setprio 0
	s_barrier
	s_add_i32 s42, s29, s16
	v_lshl_add_u64 v[228:229], s[2:3], 0, v[132:133]
	s_mov_b32 m0, s42
	ds_read_b128 v[194:197], v185 offset:16384
	ds_read_b128 v[198:201], v185 offset:17408
	ds_read_b128 v[202:205], v185 offset:18432
	ds_read_b128 v[208:211], v185 offset:19456
	ds_read_b128 v[212:215], v185 offset:20480
	ds_read_b128 v[216:219], v185 offset:21504
	ds_read_b128 v[220:223], v185 offset:22528
	ds_read_b128 v[224:227], v185 offset:23552
	global_load_lds_dwordx4 v[228:229], off
	s_add_i32 m0, s42, 0x2000
	s_add_u32 s42, s2, 0x80000
	v_lshl_add_u64 v[230:231], s[2:3], 0, v[136:137]
	s_addc_u32 s43, s3, 0
	s_add_i32 s44, s34, s16
	global_load_lds_dwordx4 v[230:231], off
	v_lshl_add_u64 v[232:233], s[42:43], 0, v[132:133]
	s_mov_b32 m0, s44
	v_lshl_add_u64 v[234:235], s[12:13], 0, v[134:135]
	global_load_lds_dwordx4 v[232:233], off
	v_lshl_add_u64 v[232:233], s[42:43], 0, v[136:137]
	s_add_i32 m0, s44, 0x2000
	s_nop 0
	global_load_lds_dwordx4 v[232:233], off
	v_lshl_add_u64 v[232:233], s[12:13], 0, v[130:131]
	s_mov_b32 m0, s17
	s_nop 0
	global_load_lds_dwordx4 v[232:233], off
	s_mov_b32 m0, s18
	s_nop 0
	global_load_lds_dwordx4 v[234:235], off
	s_waitcnt vmcnt(8)
	s_waitcnt lgkmcnt(0)
	s_barrier
	s_setprio 1
	s_waitcnt lgkmcnt(0)
	v_mfma_i32_16x16x64_i8 v[62:65], v[144:147], v[194:197], 0
	v_mfma_i32_16x16x64_i8 v[58:61], v[152:155], v[194:197], 0
	v_mfma_i32_16x16x64_i8 v[54:57], v[144:147], v[202:205], 0
	v_mfma_i32_16x16x64_i8 v[50:53], v[152:155], v[202:205], 0
	v_mfma_i32_16x16x64_i8 v[46:49], v[144:147], v[212:215], 0
	v_mfma_i32_16x16x64_i8 v[42:45], v[152:155], v[212:215], 0
	v_mfma_i32_16x16x64_i8 v[38:41], v[144:147], v[220:223], 0
	v_mfma_i32_16x16x64_i8 v[34:37], v[152:155], v[220:223], 0
	v_mfma_i32_16x16x64_i8 v[62:65], v[148:151], v[198:201], v[62:65]
	v_mfma_i32_16x16x64_i8 v[58:61], v[156:159], v[198:201], v[58:61]
	v_mfma_i32_16x16x64_i8 v[54:57], v[148:151], v[208:211], v[54:57]
	v_mfma_i32_16x16x64_i8 v[50:53], v[156:159], v[208:211], v[50:53]
	v_mfma_i32_16x16x64_i8 v[46:49], v[148:151], v[216:219], v[46:49]
	v_mfma_i32_16x16x64_i8 v[42:45], v[156:159], v[216:219], v[42:45]
	v_mfma_i32_16x16x64_i8 v[38:41], v[148:151], v[224:227], v[38:41]
	v_mfma_i32_16x16x64_i8 v[34:37], v[156:159], v[224:227], v[34:37]
	s_setprio 0
	s_setprio 1
	v_mfma_i32_16x16x64_i8 v[30:33], v[160:163], v[194:197], 0
	v_mfma_i32_16x16x64_i8 v[26:29], v[186:189], v[194:197], 0
	v_mfma_i32_16x16x64_i8 v[22:25], v[160:163], v[202:205], 0
	v_mfma_i32_16x16x64_i8 v[18:21], v[186:189], v[202:205], 0
	v_mfma_i32_16x16x64_i8 v[14:17], v[160:163], v[212:215], 0
	v_mfma_i32_16x16x64_i8 v[10:13], v[186:189], v[212:215], 0
	v_mfma_i32_16x16x64_i8 v[6:9], v[160:163], v[220:223], 0
	v_mfma_i32_16x16x64_i8 v[2:5], v[186:189], v[220:223], 0
	v_mfma_i32_16x16x64_i8 v[30:33], v[164:167], v[198:201], v[30:33]
	v_mfma_i32_16x16x64_i8 v[26:29], v[190:193], v[198:201], v[26:29]
	v_mfma_i32_16x16x64_i8 v[22:25], v[164:167], v[208:211], v[22:25]
	v_mfma_i32_16x16x64_i8 v[18:21], v[190:193], v[208:211], v[18:21]
	v_mfma_i32_16x16x64_i8 v[14:17], v[164:167], v[216:219], v[14:17]
	v_mfma_i32_16x16x64_i8 v[10:13], v[190:193], v[216:219], v[10:13]
	v_mfma_i32_16x16x64_i8 v[6:9], v[164:167], v[224:227], v[6:9]
	v_mfma_i32_16x16x64_i8 v[2:5], v[190:193], v[224:227], v[2:5]
	s_setprio 0
	s_barrier
	s_add_i32 s42, 0, 0x18000
	v_add_u32_e32 v138, s42, v183
	s_add_i32 s43, 0, 0x1c000
	ds_read_b128 v[144:147], v138
	ds_read_b128 v[148:151], v138 offset:1024
	ds_read_b128 v[152:155], v138 offset:2048
	ds_read_b128 v[156:159], v138 offset:3072
	v_add_u32_e32 v138, s43, v183
	ds_read_b128 v[160:163], v138
	ds_read_b128 v[164:167], v138 offset:1024
	ds_read_b128 v[186:189], v138 offset:2048
	ds_read_b128 v[190:193], v138 offset:3072
	s_add_u32 s12, s12, 0x80000
	s_addc_u32 s13, s13, 0
	s_mov_b32 m0, s19
	v_lshl_add_u64 v[236:237], s[12:13], 0, v[130:131]
	ds_read_b128 v[194:197], v185 offset:32768
	ds_read_b128 v[198:201], v185 offset:33792
	ds_read_b128 v[202:205], v185 offset:34816
	ds_read_b128 v[208:211], v185 offset:35840
	ds_read_b128 v[212:215], v185 offset:36864
	ds_read_b128 v[216:219], v185 offset:37888
	ds_read_b128 v[220:223], v185 offset:38912
	ds_read_b128 v[224:227], v185 offset:39936
	global_load_lds_dwordx4 v[236:237], off
	v_lshl_add_u64 v[236:237], s[12:13], 0, v[134:135]
	s_mov_b32 m0, s20
	s_nop 0
	global_load_lds_dwordx4 v[236:237], off
	s_waitcnt vmcnt(8)
	s_waitcnt lgkmcnt(0)
	s_barrier
	s_setprio 1
	s_waitcnt lgkmcnt(0)
	v_mfma_i32_16x16x64_i8 v[126:129], v[144:147], v[194:197], v[126:129]
	v_mfma_i32_16x16x64_i8 v[122:125], v[152:155], v[194:197], v[122:125]
	v_mfma_i32_16x16x64_i8 v[118:121], v[144:147], v[202:205], v[118:121]
	v_mfma_i32_16x16x64_i8 v[114:117], v[152:155], v[202:205], v[114:117]
	v_mfma_i32_16x16x64_i8 v[110:113], v[144:147], v[212:215], v[110:113]
	v_mfma_i32_16x16x64_i8 v[106:109], v[152:155], v[212:215], v[106:109]
	v_mfma_i32_16x16x64_i8 v[102:105], v[144:147], v[220:223], v[102:105]
	v_mfma_i32_16x16x64_i8 v[98:101], v[152:155], v[220:223], v[98:101]
	v_mfma_i32_16x16x64_i8 v[126:129], v[148:151], v[198:201], v[126:129]
	v_mfma_i32_16x16x64_i8 v[122:125], v[156:159], v[198:201], v[122:125]
	v_mfma_i32_16x16x64_i8 v[118:121], v[148:151], v[208:211], v[118:121]
	v_mfma_i32_16x16x64_i8 v[114:117], v[156:159], v[208:211], v[114:117]
	v_mfma_i32_16x16x64_i8 v[110:113], v[148:151], v[216:219], v[110:113]
	v_mfma_i32_16x16x64_i8 v[106:109], v[156:159], v[216:219], v[106:109]
	v_mfma_i32_16x16x64_i8 v[102:105], v[148:151], v[224:227], v[102:105]
	v_mfma_i32_16x16x64_i8 v[98:101], v[156:159], v[224:227], v[98:101]
	s_setprio 0
	s_setprio 1
	v_mfma_i32_16x16x64_i8 v[94:97], v[160:163], v[194:197], v[94:97]
	v_mfma_i32_16x16x64_i8 v[90:93], v[186:189], v[194:197], v[90:93]
	v_mfma_i32_16x16x64_i8 v[86:89], v[160:163], v[202:205], v[86:89]
	v_mfma_i32_16x16x64_i8 v[82:85], v[186:189], v[202:205], v[82:85]
	v_mfma_i32_16x16x64_i8 v[78:81], v[160:163], v[212:215], v[78:81]
	v_mfma_i32_16x16x64_i8 v[74:77], v[186:189], v[212:215], v[74:77]
	v_mfma_i32_16x16x64_i8 v[70:73], v[160:163], v[220:223], v[70:73]
	v_mfma_i32_16x16x64_i8 v[66:69], v[186:189], v[220:223], v[66:69]
	v_mfma_i32_16x16x64_i8 v[94:97], v[164:167], v[198:201], v[94:97]
	v_mfma_i32_16x16x64_i8 v[90:93], v[190:193], v[198:201], v[90:93]
	v_mfma_i32_16x16x64_i8 v[86:89], v[164:167], v[208:211], v[86:89]
	v_mfma_i32_16x16x64_i8 v[82:85], v[190:193], v[208:211], v[82:85]
	v_mfma_i32_16x16x64_i8 v[78:81], v[164:167], v[216:219], v[78:81]
	v_mfma_i32_16x16x64_i8 v[74:77], v[190:193], v[216:219], v[74:77]
	v_mfma_i32_16x16x64_i8 v[70:73], v[164:167], v[224:227], v[70:73]
	v_mfma_i32_16x16x64_i8 v[66:69], v[190:193], v[224:227], v[66:69]
	s_setprio 0
	s_barrier
	s_add_i32 s12, s42, s16
	v_lshl_add_u64 v[228:229], v[228:229], 0, s[10:11]
	s_mov_b32 m0, s12
	ds_read_b128 v[194:197], v185 offset:49152
	ds_read_b128 v[198:201], v185 offset:50176
	ds_read_b128 v[202:205], v185 offset:51200
	ds_read_b128 v[208:211], v185 offset:52224
	ds_read_b128 v[212:215], v185 offset:53248
	ds_read_b128 v[216:219], v185 offset:54272
	ds_read_b128 v[220:223], v185 offset:55296
	ds_read_b128 v[224:227], v185 offset:56320
	global_load_lds_dwordx4 v[228:229], off
	s_add_i32 m0, s12, 0x2000
	s_add_u32 s2, s2, 0x80080
	v_lshl_add_u64 v[228:229], v[230:231], 0, s[10:11]
	s_addc_u32 s3, s3, 0
	s_add_i32 s12, s43, s16
	global_load_lds_dwordx4 v[228:229], off
	v_lshl_add_u64 v[228:229], s[2:3], 0, v[132:133]
	s_mov_b32 m0, s12
	s_nop 0
	global_load_lds_dwordx4 v[228:229], off
	v_lshl_add_u64 v[228:229], s[2:3], 0, v[136:137]
	s_add_i32 m0, s12, 0x2000
	s_nop 0
	global_load_lds_dwordx4 v[228:229], off
	v_lshl_add_u64 v[228:229], v[232:233], 0, s[10:11]
	s_mov_b32 m0, s22
	s_nop 0
	global_load_lds_dwordx4 v[228:229], off
	v_lshl_add_u64 v[228:229], v[234:235], 0, s[10:11]
	s_mov_b32 m0, s23
	s_nop 0
	global_load_lds_dwordx4 v[228:229], off
	s_waitcnt vmcnt(8)
	s_waitcnt lgkmcnt(0)
	s_barrier
	s_setprio 1
	s_waitcnt lgkmcnt(0)
	v_mfma_i32_16x16x64_i8 v[62:65], v[144:147], v[194:197], v[62:65]
	v_mfma_i32_16x16x64_i8 v[58:61], v[152:155], v[194:197], v[58:61]
	v_mfma_i32_16x16x64_i8 v[54:57], v[144:147], v[202:205], v[54:57]
	v_mfma_i32_16x16x64_i8 v[50:53], v[152:155], v[202:205], v[50:53]
	v_mfma_i32_16x16x64_i8 v[46:49], v[144:147], v[212:215], v[46:49]
	v_mfma_i32_16x16x64_i8 v[42:45], v[152:155], v[212:215], v[42:45]
	v_mfma_i32_16x16x64_i8 v[38:41], v[144:147], v[220:223], v[38:41]
	v_mfma_i32_16x16x64_i8 v[34:37], v[152:155], v[220:223], v[34:37]
	v_mfma_i32_16x16x64_i8 v[62:65], v[148:151], v[198:201], v[62:65]
	v_mfma_i32_16x16x64_i8 v[58:61], v[156:159], v[198:201], v[58:61]
	v_mfma_i32_16x16x64_i8 v[54:57], v[148:151], v[208:211], v[54:57]
	v_mfma_i32_16x16x64_i8 v[50:53], v[156:159], v[208:211], v[50:53]
	v_mfma_i32_16x16x64_i8 v[46:49], v[148:151], v[216:219], v[46:49]
	v_mfma_i32_16x16x64_i8 v[42:45], v[156:159], v[216:219], v[42:45]
	v_mfma_i32_16x16x64_i8 v[38:41], v[148:151], v[224:227], v[38:41]
	v_mfma_i32_16x16x64_i8 v[34:37], v[156:159], v[224:227], v[34:37]
	s_setprio 0
	s_setprio 1
	v_mfma_i32_16x16x64_i8 v[30:33], v[160:163], v[194:197], v[30:33]
	v_mfma_i32_16x16x64_i8 v[26:29], v[186:189], v[194:197], v[26:29]
	v_mfma_i32_16x16x64_i8 v[22:25], v[160:163], v[202:205], v[22:25]
	v_mfma_i32_16x16x64_i8 v[18:21], v[186:189], v[202:205], v[18:21]
	v_mfma_i32_16x16x64_i8 v[14:17], v[160:163], v[212:215], v[14:17]
	v_mfma_i32_16x16x64_i8 v[10:13], v[186:189], v[212:215], v[10:13]
	v_mfma_i32_16x16x64_i8 v[6:9], v[160:163], v[220:223], v[6:9]
	v_mfma_i32_16x16x64_i8 v[2:5], v[186:189], v[220:223], v[2:5]
	v_mfma_i32_16x16x64_i8 v[30:33], v[164:167], v[198:201], v[30:33]
	v_mfma_i32_16x16x64_i8 v[26:29], v[190:193], v[198:201], v[26:29]
	v_mfma_i32_16x16x64_i8 v[22:25], v[164:167], v[208:211], v[22:25]
	v_mfma_i32_16x16x64_i8 v[18:21], v[190:193], v[208:211], v[18:21]
	v_mfma_i32_16x16x64_i8 v[14:17], v[164:167], v[216:219], v[14:17]
	v_mfma_i32_16x16x64_i8 v[10:13], v[190:193], v[216:219], v[10:13]
	v_mfma_i32_16x16x64_i8 v[6:9], v[164:167], v[224:227], v[6:9]
	v_mfma_i32_16x16x64_i8 v[2:5], v[190:193], v[224:227], v[2:5]
	s_setprio 0
	s_barrier
	s_add_u32 s4, s4, 0x100
	s_addc_u32 s5, s5, 0
	s_add_u32 s39, s39, 0x100
	s_addc_u32 s40, s40, 0
	s_cmp_ge_i32 s41, s1
	s_mov_b32 s2, s41
	s_cbranch_scc1 .Lkpeel_exit_0

.Lkpeel_exit_0:
	v_cvt_f32_i32_e32 v166, v126
	v_cvt_f32_i32_e32 v167, v127
	v_cvt_f32_i32_e32 v164, v128
	v_cvt_f32_i32_e32 v165, v129
	v_cvt_f32_i32_e32 v162, v122
	v_cvt_f32_i32_e32 v163, v123
	v_cvt_f32_i32_e32 v158, v124
	v_cvt_f32_i32_e32 v159, v125
	v_cvt_f32_i32_e32 v150, v118
	v_cvt_f32_i32_e32 v151, v119
	v_cvt_f32_i32_e32 v148, v120
	v_cvt_f32_i32_e32 v149, v121
	v_cvt_f32_i32_e32 v146, v114
	v_cvt_f32_i32_e32 v147, v115
	v_cvt_f32_i32_e32 v128, v116
	v_cvt_f32_i32_e32 v129, v117
	v_cvt_f32_i32_e32 v118, v110
	v_cvt_f32_i32_e32 v119, v111
	v_cvt_f32_i32_e32 v116, v112
	v_cvt_f32_i32_e32 v117, v113
	v_cvt_f32_i32_e32 v114, v106
	v_cvt_f32_i32_e32 v115, v107
	v_cvt_f32_i32_e32 v110, v108
	v_cvt_f32_i32_e32 v111, v109
	v_cvt_f32_i32_e32 v106, v102
	v_cvt_f32_i32_e32 v107, v103
	v_cvt_f32_i32_e32 v104, v104
	v_cvt_f32_i32_e32 v105, v105
	v_cvt_f32_i32_e32 v102, v98
	v_cvt_f32_i32_e32 v103, v99
	v_cvt_f32_i32_e32 v98, v100
	v_cvt_f32_i32_e32 v99, v101
	v_cvt_f32_i32_e32 v160, v94
	v_cvt_f32_i32_e32 v161, v95
	v_cvt_f32_i32_e32 v156, v96
	v_cvt_f32_i32_e32 v157, v97
	v_cvt_f32_i32_e32 v154, v90
	v_cvt_f32_i32_e32 v155, v91
	v_cvt_f32_i32_e32 v152, v92
	v_cvt_f32_i32_e32 v153, v93
	v_cvt_f32_i32_e32 v144, v86
	v_cvt_f32_i32_e32 v145, v87
	v_cvt_f32_i32_e32 v126, v88
	v_cvt_f32_i32_e32 v127, v89
	v_cvt_f32_i32_e32 v124, v82
	v_cvt_f32_i32_e32 v125, v83
	v_cvt_f32_i32_e32 v122, v84
	v_cvt_f32_i32_e32 v123, v85
	v_cvt_f32_i32_e32 v112, v78
	v_cvt_f32_i32_e32 v113, v79
	v_cvt_f32_i32_e32 v108, v80
	v_cvt_f32_i32_e32 v109, v81
	v_cvt_f32_i32_e32 v100, v74
	v_cvt_f32_i32_e32 v101, v75
	v_cvt_f32_i32_e32 v96, v76
	v_cvt_f32_i32_e32 v97, v77
	v_cvt_f32_i32_e32 v92, v70
	v_cvt_f32_i32_e32 v93, v71
	v_cvt_f32_i32_e32 v90, v72
	v_cvt_f32_i32_e32 v91, v73
	v_cvt_f32_i32_e32 v88, v66
	v_cvt_f32_i32_e32 v89, v67
	v_cvt_f32_i32_e32 v86, v68
	v_cvt_f32_i32_e32 v87, v69
	v_cvt_f32_i32_e32 v84, v62
	v_cvt_f32_i32_e32 v85, v63
	v_cvt_f32_i32_e32 v82, v64
	v_cvt_f32_i32_e32 v83, v65
	v_cvt_f32_i32_e32 v80, v58
	v_cvt_f32_i32_e32 v81, v59
	v_cvt_f32_i32_e32 v76, v60
	v_cvt_f32_i32_e32 v77, v61
	v_cvt_f32_i32_e32 v66, v54
	v_cvt_f32_i32_e32 v67, v55
	v_cvt_f32_i32_e32 v64, v56
	v_cvt_f32_i32_e32 v65, v57
	v_cvt_f32_i32_e32 v62, v50
	v_cvt_f32_i32_e32 v63, v51
	v_cvt_f32_i32_e32 v58, v52
	v_cvt_f32_i32_e32 v59, v53
	v_cvt_f32_i32_e32 v50, v46
	v_cvt_f32_i32_e32 v51, v47
	v_cvt_f32_i32_e32 v48, v48
	v_cvt_f32_i32_e32 v49, v49
	v_cvt_f32_i32_e32 v46, v42
	v_cvt_f32_i32_e32 v47, v43
	v_cvt_f32_i32_e32 v44, v44
	v_cvt_f32_i32_e32 v45, v45
	v_cvt_f32_i32_e32 v42, v38
	v_cvt_f32_i32_e32 v43, v39
	v_cvt_f32_i32_e32 v40, v40
	v_cvt_f32_i32_e32 v41, v41
	v_cvt_f32_i32_e32 v38, v34
	v_cvt_f32_i32_e32 v39, v35
	v_cvt_f32_i32_e32 v34, v36
	v_cvt_f32_i32_e32 v35, v37
	v_cvt_f32_i32_e32 v78, v30
	v_cvt_f32_i32_e32 v79, v31
	v_cvt_f32_i32_e32 v74, v32
	v_cvt_f32_i32_e32 v75, v33
	v_cvt_f32_i32_e32 v70, v26
	v_cvt_f32_i32_e32 v71, v27
	v_cvt_f32_i32_e32 v68, v28
	v_cvt_f32_i32_e32 v69, v29
	v_cvt_f32_i32_e32 v60, v22
	v_cvt_f32_i32_e32 v61, v23
	v_cvt_f32_i32_e32 v56, v24
	v_cvt_f32_i32_e32 v57, v25
	v_cvt_f32_i32_e32 v54, v18
	v_cvt_f32_i32_e32 v55, v19
	v_cvt_f32_i32_e32 v36, v20
	v_cvt_f32_i32_e32 v37, v21
	v_cvt_f32_i32_e32 v32, v14
	v_cvt_f32_i32_e32 v33, v15
	v_cvt_f32_i32_e32 v30, v16
	v_cvt_f32_i32_e32 v31, v17
	v_cvt_f32_i32_e32 v28, v10
	v_cvt_f32_i32_e32 v29, v11
	v_cvt_f32_i32_e32 v26, v12
	v_cvt_f32_i32_e32 v27, v13
	v_cvt_f32_i32_e32 v24, v6
	v_cvt_f32_i32_e32 v25, v7
	v_cvt_f32_i32_e32 v22, v8
	v_cvt_f32_i32_e32 v23, v9
	v_cvt_f32_i32_e32 v20, v2
	v_cvt_f32_i32_e32 v21, v3
	v_cvt_f32_i32_e32 v18, v4
	v_cvt_f32_i32_e32 v19, v5
	s_and_b64 vcc, exec, s[26:27]
	s_cbranch_vccz .LBB0_248

.LBB0_265:
	s_lshl_b32 s10, s8, 21
	s_and_b32 s10, s10, 0x1fe00000
	v_readlane_b32 s40, v248, 20
	v_readlane_b32 s41, v248, 21
	s_add_u32 s10, s40, s10
	s_addc_u32 s33, s41, 0
	s_lshr_b32 s39, s8, 13
	s_and_b32 s39, s39, 0x7ff80
	s_add_u32 s70, s10, s39
	s_addc_u32 s71, s33, 0
	s_lshl_b32 s10, s8, 13
	s_and_b32 s10, s10, 0x1fe00000
	v_readlane_b32 s40, v248, 18
	v_readlane_b32 s41, v248, 19
	s_add_u32 s10, s40, s10
	s_addc_u32 s33, s41, 0
	s_add_u32 s72, s10, s39
	s_addc_u32 s73, s33, 0
	s_cmp_lt_i32 s1, 1
	v_cmp_gt_i64_e64 s[74:75], s[8:9], -1
	s_cbranch_scc1 .LBB0_324
	s_and_b64 s[8:9], s[74:75], exec
	s_cselect_b32 s10, s71, s5
	s_cselect_b32 s33, s70, s4
	s_cselect_b32 s39, s73, s3
	s_cselect_b32 s40, s72, s2
	s_add_i32 s41, s1, -2
	s_add_u32 s4, s4, 0x100080
	s_addc_u32 s5, s5, 0
	s_add_u32 s42, s2, 0x100
	s_addc_u32 s43, s3, 0
	s_mov_b32 s2, 0
	ds_read_b128 v[148:151], v145
	ds_read_b128 v[152:155], v145 offset:1024
	ds_read_b128 v[156:159], v145 offset:2048
	ds_read_b128 v[160:163], v145 offset:3072
	ds_read_b128 v[164:167], v146
	ds_read_b128 v[168:171], v146 offset:1024
	ds_read_b128 v[172:175], v146 offset:2048
	ds_read_b128 v[176:179], v146 offset:3072
	s_add_i32 s44, s2, 2
	s_add_u32 s3, s4, 0xfff00080
	s_addc_u32 s8, s5, -1
	s_cmp_eq_u32 s41, s2
	s_cselect_b32 s2, s40, s42
	s_cselect_b32 s9, s10, s8
	s_cselect_b32 s8, s33, s3
	s_cselect_b32 s3, s39, s43
	v_lshl_add_u64 v[204:205], s[4:5], 0, v[138:139]
	s_add_i32 m0, s16, 0xc000
	ds_read_b128 v[180:183], v147
	ds_read_b128 v[184:187], v147 offset:1024
	ds_read_b128 v[188:191], v147 offset:2048
	ds_read_b128 v[192:195], v147 offset:3072
	ds_read_b128 v[196:199], v147 offset:4096
	ds_read_b128 v[200:203], v147 offset:5120
	ds_read_b128 v[208:211], v147 offset:6144
	ds_read_b128 v[212:215], v147 offset:7168
	global_load_lds_dwordx4 v[204:205], off
	v_lshl_add_u64 v[204:205], s[4:5], 0, v[140:141]
	s_add_i32 m0, s16, 0xe000
	s_nop 0
	global_load_lds_dwordx4 v[204:205], off
	s_waitcnt vmcnt(8)
	s_waitcnt lgkmcnt(0)
	s_barrier
	s_setprio 1
	s_waitcnt lgkmcnt(0)
	v_mfma_f32_16x16x32_bf16 v[122:125], v[148:151], v[180:183], 0
	v_mfma_f32_16x16x32_bf16 v[118:121], v[156:159], v[180:183], 0
	v_mfma_f32_16x16x32_bf16 v[110:113], v[148:151], v[188:191], 0
	v_mfma_f32_16x16x32_bf16 v[102:105], v[156:159], v[188:191], 0
	v_mfma_f32_16x16x32_bf16 v[94:97], v[148:151], v[196:199], 0
	v_mfma_f32_16x16x32_bf16 v[86:89], v[156:159], v[196:199], 0
	v_mfma_f32_16x16x32_bf16 v[78:81], v[148:151], v[208:211], 0
	v_mfma_f32_16x16x32_bf16 v[70:73], v[156:159], v[208:211], 0
	v_mfma_f32_16x16x32_bf16 v[122:125], v[152:155], v[184:187], v[122:125]
	v_mfma_f32_16x16x32_bf16 v[118:121], v[160:163], v[184:187], v[118:121]
	v_mfma_f32_16x16x32_bf16 v[110:113], v[152:155], v[192:195], v[110:113]
	v_mfma_f32_16x16x32_bf16 v[102:105], v[160:163], v[192:195], v[102:105]
	v_mfma_f32_16x16x32_bf16 v[94:97], v[152:155], v[200:203], v[94:97]
	v_mfma_f32_16x16x32_bf16 v[86:89], v[160:163], v[200:203], v[86:89]
	v_mfma_f32_16x16x32_bf16 v[78:81], v[152:155], v[212:215], v[78:81]
	v_mfma_f32_16x16x32_bf16 v[70:73], v[160:163], v[212:215], v[70:73]
	s_setprio 0
	s_setprio 1
	v_mfma_f32_16x16x32_bf16 v[126:129], v[164:167], v[180:183], 0
	v_mfma_f32_16x16x32_bf16 v[114:117], v[172:175], v[180:183], 0
	v_mfma_f32_16x16x32_bf16 v[106:109], v[164:167], v[188:191], 0
	v_mfma_f32_16x16x32_bf16 v[98:101], v[172:175], v[188:191], 0
	v_mfma_f32_16x16x32_bf16 v[90:93], v[164:167], v[196:199], 0
	v_mfma_f32_16x16x32_bf16 v[82:85], v[172:175], v[196:199], 0
	v_mfma_f32_16x16x32_bf16 v[74:77], v[164:167], v[208:211], 0
	v_mfma_f32_16x16x32_bf16 v[66:69], v[172:175], v[208:211], 0
	v_mfma_f32_16x16x32_bf16 v[126:129], v[168:171], v[184:187], v[126:129]
	v_mfma_f32_16x16x32_bf16 v[114:117], v[176:179], v[184:187], v[114:117]
	v_mfma_f32_16x16x32_bf16 v[106:109], v[168:171], v[192:195], v[106:109]
	v_mfma_f32_16x16x32_bf16 v[98:101], v[176:179], v[192:195], v[98:101]
	v_mfma_f32_16x16x32_bf16 v[90:93], v[168:171], v[200:203], v[90:93]
	v_mfma_f32_16x16x32_bf16 v[82:85], v[176:179], v[200:203], v[82:85]
	v_mfma_f32_16x16x32_bf16 v[74:77], v[168:171], v[212:215], v[74:77]
	v_mfma_f32_16x16x32_bf16 v[66:69], v[176:179], v[212:215], v[66:69]
	s_setprio 0
	s_barrier
	s_add_i32 s45, s36, s13
	v_lshl_add_u64 v[204:205], s[2:3], 0, v[132:133]
	s_mov_b32 m0, s45
	ds_read_b128 v[180:183], v147 offset:16384
	ds_read_b128 v[184:187], v147 offset:17408
	ds_read_b128 v[188:191], v147 offset:18432
	ds_read_b128 v[192:195], v147 offset:19456
	ds_read_b128 v[196:199], v147 offset:20480
	ds_read_b128 v[200:203], v147 offset:21504
	ds_read_b128 v[208:211], v147 offset:22528
	ds_read_b128 v[212:215], v147 offset:23552
	global_load_lds_dwordx4 v[204:205], off
	s_add_i32 m0, s45, 0x2000
	s_add_u32 s46, s2, 0x100000
	v_lshl_add_u64 v[216:217], s[2:3], 0, v[136:137]
	s_addc_u32 s47, s3, 0
	s_add_i32 s45, s37, s13
	global_load_lds_dwordx4 v[216:217], off
	v_lshl_add_u64 v[218:219], s[46:47], 0, v[132:133]
	s_mov_b32 m0, s45
	v_lshl_add_u64 v[220:221], s[8:9], 0, v[134:135]
	global_load_lds_dwordx4 v[218:219], off
	v_lshl_add_u64 v[218:219], s[46:47], 0, v[136:137]
	s_add_i32 m0, s45, 0x2000
	s_nop 0
	global_load_lds_dwordx4 v[218:219], off
	v_lshl_add_u64 v[218:219], s[8:9], 0, v[130:131]
	s_mov_b32 m0, s16
	s_nop 0
	global_load_lds_dwordx4 v[218:219], off
	s_mov_b32 m0, s17
	s_nop 0
	global_load_lds_dwordx4 v[220:221], off
	s_waitcnt vmcnt(8)
	s_waitcnt lgkmcnt(0)
	s_barrier
	s_setprio 1
	s_waitcnt lgkmcnt(0)
	v_mfma_f32_16x16x32_bf16 v[62:65], v[148:151], v[180:183], 0
	v_mfma_f32_16x16x32_bf16 v[54:57], v[156:159], v[180:183], 0
	v_mfma_f32_16x16x32_bf16 v[46:49], v[148:151], v[188:191], 0
	v_mfma_f32_16x16x32_bf16 v[38:41], v[156:159], v[188:191], 0
	v_mfma_f32_16x16x32_bf16 v[30:33], v[148:151], v[196:199], 0
	v_mfma_f32_16x16x32_bf16 v[22:25], v[156:159], v[196:199], 0
	v_mfma_f32_16x16x32_bf16 v[14:17], v[148:151], v[208:211], 0
	v_mfma_f32_16x16x32_bf16 v[6:9], v[156:159], v[208:211], 0
	v_mfma_f32_16x16x32_bf16 v[62:65], v[152:155], v[184:187], v[62:65]
	v_mfma_f32_16x16x32_bf16 v[54:57], v[160:163], v[184:187], v[54:57]
	v_mfma_f32_16x16x32_bf16 v[46:49], v[152:155], v[192:195], v[46:49]
	v_mfma_f32_16x16x32_bf16 v[38:41], v[160:163], v[192:195], v[38:41]
	v_mfma_f32_16x16x32_bf16 v[30:33], v[152:155], v[200:203], v[30:33]
	v_mfma_f32_16x16x32_bf16 v[22:25], v[160:163], v[200:203], v[22:25]
	v_mfma_f32_16x16x32_bf16 v[14:17], v[152:155], v[212:215], v[14:17]
	v_mfma_f32_16x16x32_bf16 v[6:9], v[160:163], v[212:215], v[6:9]
	s_setprio 0
	s_setprio 1
	v_mfma_f32_16x16x32_bf16 v[58:61], v[164:167], v[180:183], 0
	v_mfma_f32_16x16x32_bf16 v[50:53], v[172:175], v[180:183], 0
	v_mfma_f32_16x16x32_bf16 v[42:45], v[164:167], v[188:191], 0
	v_mfma_f32_16x16x32_bf16 v[34:37], v[172:175], v[188:191], 0
	v_mfma_f32_16x16x32_bf16 v[26:29], v[164:167], v[196:199], 0
	v_mfma_f32_16x16x32_bf16 v[18:21], v[172:175], v[196:199], 0
	v_mfma_f32_16x16x32_bf16 v[10:13], v[164:167], v[208:211], 0
	v_mfma_f32_16x16x32_bf16 v[2:5], v[172:175], v[208:211], 0
	v_mfma_f32_16x16x32_bf16 v[58:61], v[168:171], v[184:187], v[58:61]
	v_mfma_f32_16x16x32_bf16 v[50:53], v[176:179], v[184:187], v[50:53]
	v_mfma_f32_16x16x32_bf16 v[42:45], v[168:171], v[192:195], v[42:45]
	v_mfma_f32_16x16x32_bf16 v[34:37], v[176:179], v[192:195], v[34:37]
	v_mfma_f32_16x16x32_bf16 v[26:29], v[168:171], v[200:203], v[26:29]
	v_mfma_f32_16x16x32_bf16 v[18:21], v[176:179], v[200:203], v[18:21]
	v_mfma_f32_16x16x32_bf16 v[10:13], v[168:171], v[212:215], v[10:13]
	v_mfma_f32_16x16x32_bf16 v[2:5], v[176:179], v[212:215], v[2:5]
	s_setprio 0
	s_barrier
	s_add_i32 s45, 0, 0x18000
	s_add_i32 s46, 0, 0x1c000
	v_add_u32_e32 v160, s45, v1
	v_add_u32_e32 v176, s46, v1
	ds_read_b128 v[148:151], v160
	ds_read_b128 v[152:155], v160 offset:1024
	ds_read_b128 v[156:159], v160 offset:2048
	ds_read_b128 v[160:163], v160 offset:3072
	ds_read_b128 v[164:167], v176
	ds_read_b128 v[168:171], v176 offset:1024
	ds_read_b128 v[172:175], v176 offset:2048
	ds_read_b128 v[176:179], v176 offset:3072
	s_add_u32 s8, s8, 0x100000
	s_addc_u32 s9, s9, 0
	s_mov_b32 m0, s18
	v_lshl_add_u64 v[222:223], s[8:9], 0, v[130:131]
	ds_read_b128 v[180:183], v147 offset:32768
	ds_read_b128 v[184:187], v147 offset:33792
	ds_read_b128 v[188:191], v147 offset:34816
	ds_read_b128 v[192:195], v147 offset:35840
	ds_read_b128 v[196:199], v147 offset:36864
	ds_read_b128 v[200:203], v147 offset:37888
	ds_read_b128 v[208:211], v147 offset:38912
	ds_read_b128 v[212:215], v147 offset:39936
	global_load_lds_dwordx4 v[222:223], off
	v_lshl_add_u64 v[222:223], s[8:9], 0, v[134:135]
	s_mov_b32 m0, s19
	s_nop 0
	global_load_lds_dwordx4 v[222:223], off
	s_waitcnt vmcnt(8)
	s_waitcnt lgkmcnt(0)
	s_barrier
	s_setprio 1
	s_waitcnt lgkmcnt(0)
	v_mfma_f32_16x16x32_bf16 v[122:125], v[148:151], v[180:183], v[122:125]
	v_mfma_f32_16x16x32_bf16 v[118:121], v[156:159], v[180:183], v[118:121]
	v_mfma_f32_16x16x32_bf16 v[110:113], v[148:151], v[188:191], v[110:113]
	v_mfma_f32_16x16x32_bf16 v[102:105], v[156:159], v[188:191], v[102:105]
	v_mfma_f32_16x16x32_bf16 v[94:97], v[148:151], v[196:199], v[94:97]
	v_mfma_f32_16x16x32_bf16 v[86:89], v[156:159], v[196:199], v[86:89]
	v_mfma_f32_16x16x32_bf16 v[78:81], v[148:151], v[208:211], v[78:81]
	v_mfma_f32_16x16x32_bf16 v[70:73], v[156:159], v[208:211], v[70:73]
	v_mfma_f32_16x16x32_bf16 v[122:125], v[152:155], v[184:187], v[122:125]
	v_mfma_f32_16x16x32_bf16 v[118:121], v[160:163], v[184:187], v[118:121]
	v_mfma_f32_16x16x32_bf16 v[110:113], v[152:155], v[192:195], v[110:113]
	v_mfma_f32_16x16x32_bf16 v[102:105], v[160:163], v[192:195], v[102:105]
	v_mfma_f32_16x16x32_bf16 v[94:97], v[152:155], v[200:203], v[94:97]
	v_mfma_f32_16x16x32_bf16 v[86:89], v[160:163], v[200:203], v[86:89]
	v_mfma_f32_16x16x32_bf16 v[78:81], v[152:155], v[212:215], v[78:81]
	v_mfma_f32_16x16x32_bf16 v[70:73], v[160:163], v[212:215], v[70:73]
	s_setprio 0
	s_setprio 1
	v_mfma_f32_16x16x32_bf16 v[126:129], v[164:167], v[180:183], v[126:129]
	v_mfma_f32_16x16x32_bf16 v[114:117], v[172:175], v[180:183], v[114:117]
	v_mfma_f32_16x16x32_bf16 v[106:109], v[164:167], v[188:191], v[106:109]
	v_mfma_f32_16x16x32_bf16 v[98:101], v[172:175], v[188:191], v[98:101]
	v_mfma_f32_16x16x32_bf16 v[90:93], v[164:167], v[196:199], v[90:93]
	v_mfma_f32_16x16x32_bf16 v[82:85], v[172:175], v[196:199], v[82:85]
	v_mfma_f32_16x16x32_bf16 v[74:77], v[164:167], v[208:211], v[74:77]
	v_mfma_f32_16x16x32_bf16 v[66:69], v[172:175], v[208:211], v[66:69]
	v_mfma_f32_16x16x32_bf16 v[126:129], v[168:171], v[184:187], v[126:129]
	v_mfma_f32_16x16x32_bf16 v[114:117], v[176:179], v[184:187], v[114:117]
	v_mfma_f32_16x16x32_bf16 v[106:109], v[168:171], v[192:195], v[106:109]
	v_mfma_f32_16x16x32_bf16 v[98:101], v[176:179], v[192:195], v[98:101]
	v_mfma_f32_16x16x32_bf16 v[90:93], v[168:171], v[200:203], v[90:93]
	v_mfma_f32_16x16x32_bf16 v[82:85], v[176:179], v[200:203], v[82:85]
	v_mfma_f32_16x16x32_bf16 v[74:77], v[168:171], v[212:215], v[74:77]
	v_mfma_f32_16x16x32_bf16 v[66:69], v[176:179], v[212:215], v[66:69]
	s_setprio 0
	s_barrier
	s_add_i32 s8, s45, s13
	v_lshl_add_u64 v[204:205], v[204:205], 0, s[24:25]
	s_mov_b32 m0, s8
	ds_read_b128 v[180:183], v147 offset:49152
	ds_read_b128 v[184:187], v147 offset:50176
	ds_read_b128 v[188:191], v147 offset:51200
	ds_read_b128 v[192:195], v147 offset:52224
	ds_read_b128 v[196:199], v147 offset:53248
	ds_read_b128 v[200:203], v147 offset:54272
	ds_read_b128 v[208:211], v147 offset:55296
	ds_read_b128 v[212:215], v147 offset:56320
	global_load_lds_dwordx4 v[204:205], off
	s_add_i32 m0, s8, 0x2000
	s_add_u32 s2, s2, 0x100080
	v_lshl_add_u64 v[204:205], v[216:217], 0, s[24:25]
	s_addc_u32 s3, s3, 0
	s_add_i32 s8, s46, s13
	global_load_lds_dwordx4 v[204:205], off
	v_lshl_add_u64 v[204:205], s[2:3], 0, v[132:133]
	s_mov_b32 m0, s8
	s_nop 0
	global_load_lds_dwordx4 v[204:205], off
	v_lshl_add_u64 v[204:205], s[2:3], 0, v[136:137]
	s_add_i32 m0, s8, 0x2000
	s_nop 0
	global_load_lds_dwordx4 v[204:205], off
	v_lshl_add_u64 v[204:205], v[218:219], 0, s[24:25]
	s_mov_b32 m0, s29
	s_nop 0
	global_load_lds_dwordx4 v[204:205], off
	v_lshl_add_u64 v[204:205], v[220:221], 0, s[24:25]
	s_mov_b32 m0, s34
	s_nop 0
	global_load_lds_dwordx4 v[204:205], off
	s_waitcnt vmcnt(8)
	s_waitcnt lgkmcnt(0)
	s_barrier
	s_setprio 1
	s_waitcnt lgkmcnt(0)
	v_mfma_f32_16x16x32_bf16 v[62:65], v[148:151], v[180:183], v[62:65]
	v_mfma_f32_16x16x32_bf16 v[54:57], v[156:159], v[180:183], v[54:57]
	v_mfma_f32_16x16x32_bf16 v[46:49], v[148:151], v[188:191], v[46:49]
	v_mfma_f32_16x16x32_bf16 v[38:41], v[156:159], v[188:191], v[38:41]
	v_mfma_f32_16x16x32_bf16 v[30:33], v[148:151], v[196:199], v[30:33]
	v_mfma_f32_16x16x32_bf16 v[22:25], v[156:159], v[196:199], v[22:25]
	v_mfma_f32_16x16x32_bf16 v[14:17], v[148:151], v[208:211], v[14:17]
	v_mfma_f32_16x16x32_bf16 v[6:9], v[156:159], v[208:211], v[6:9]
	v_mfma_f32_16x16x32_bf16 v[62:65], v[152:155], v[184:187], v[62:65]
	v_mfma_f32_16x16x32_bf16 v[54:57], v[160:163], v[184:187], v[54:57]
	v_mfma_f32_16x16x32_bf16 v[46:49], v[152:155], v[192:195], v[46:49]
	v_mfma_f32_16x16x32_bf16 v[38:41], v[160:163], v[192:195], v[38:41]
	v_mfma_f32_16x16x32_bf16 v[30:33], v[152:155], v[200:203], v[30:33]
	v_mfma_f32_16x16x32_bf16 v[22:25], v[160:163], v[200:203], v[22:25]
	v_mfma_f32_16x16x32_bf16 v[14:17], v[152:155], v[212:215], v[14:17]
	v_mfma_f32_16x16x32_bf16 v[6:9], v[160:163], v[212:215], v[6:9]
	s_setprio 0
	s_setprio 1
	v_mfma_f32_16x16x32_bf16 v[58:61], v[164:167], v[180:183], v[58:61]
	v_mfma_f32_16x16x32_bf16 v[50:53], v[172:175], v[180:183], v[50:53]
	v_mfma_f32_16x16x32_bf16 v[42:45], v[164:167], v[188:191], v[42:45]
	v_mfma_f32_16x16x32_bf16 v[34:37], v[172:175], v[188:191], v[34:37]
	v_mfma_f32_16x16x32_bf16 v[26:29], v[164:167], v[196:199], v[26:29]
	v_mfma_f32_16x16x32_bf16 v[18:21], v[172:175], v[196:199], v[18:21]
	v_mfma_f32_16x16x32_bf16 v[10:13], v[164:167], v[208:211], v[10:13]
	v_mfma_f32_16x16x32_bf16 v[2:5], v[172:175], v[208:211], v[2:5]
	v_mfma_f32_16x16x32_bf16 v[58:61], v[168:171], v[184:187], v[58:61]
	v_mfma_f32_16x16x32_bf16 v[50:53], v[176:179], v[184:187], v[50:53]
	v_mfma_f32_16x16x32_bf16 v[42:45], v[168:171], v[192:195], v[42:45]
	v_mfma_f32_16x16x32_bf16 v[34:37], v[176:179], v[192:195], v[34:37]
	v_mfma_f32_16x16x32_bf16 v[26:29], v[168:171], v[200:203], v[26:29]
	v_mfma_f32_16x16x32_bf16 v[18:21], v[176:179], v[200:203], v[18:21]
	v_mfma_f32_16x16x32_bf16 v[10:13], v[168:171], v[212:215], v[10:13]
	v_mfma_f32_16x16x32_bf16 v[2:5], v[176:179], v[212:215], v[2:5]
	s_setprio 0
	s_barrier
	s_add_u32 s4, s4, 0x100
	s_addc_u32 s5, s5, 0
	s_add_u32 s42, s42, 0x100
	s_addc_u32 s43, s43, 0
	s_cmp_ge_i32 s44, s1
	s_mov_b32 s2, s44
	s_cbranch_scc1 .Lkpeel_exit_1

.Lkpeel_exit_1:
	s_and_b64 vcc, exec, s[26:27]
	s_cbranch_vccz .LBB0_270

.LBB0_524:
	s_lshl_b32 s0, s26, 20
	s_and_b32 s0, s0, 0xff00000
	s_add_u32 s0, s70, s0
	s_addc_u32 s23, s71, 0
	s_lshr_b32 s22, s26, 13
	s_and_b32 s24, s22, 0x7ff80
	s_add_u32 s22, s0, s24
	s_addc_u32 s23, s23, 0
	s_lshl_b32 s0, s26, 12
	s_and_b32 s0, s0, 0xff00000
	s_add_u32 s0, s30, s0
	s_addc_u32 s25, s31, 0
	s_add_u32 s24, s0, s24
	s_addc_u32 s25, s25, 0
	s_cmp_lt_i32 s37, 1
	v_cmp_gt_i64_e64 s[26:27], s[26:27], -1
	s_cbranch_scc1 .LBB0_546
	s_and_b64 s[40:41], s[26:27], exec
	s_cselect_b32 s0, s23, s39
	s_cselect_b32 s36, s22, s38
	s_cselect_b32 s65, s25, s3
	s_cselect_b32 s66, s24, s2
	s_add_i32 s67, s37, -2
	s_add_u32 s38, s38, 0x80080
	s_addc_u32 s39, s39, 0
	s_add_u32 s68, s2, 0x100
	s_addc_u32 s69, s3, 0
	s_mov_b32 s2, 0
	ds_read_b128 v[148:151], v144
	ds_read_b128 v[152:155], v144 offset:1024
	ds_read_b128 v[156:159], v144 offset:2048
	ds_read_b128 v[160:163], v144 offset:3072
	ds_read_b128 v[164:167], v145
	ds_read_b128 v[168:171], v145 offset:1024
	ds_read_b128 v[172:175], v145 offset:2048
	ds_read_b128 v[176:179], v145 offset:3072
	s_waitcnt lgkmcnt(0)
	s_add_i32 s72, s2, 2
	s_add_u32 s3, s38, 0xfff80080
	s_addc_u32 s40, s39, -1
	s_cmp_eq_u32 s67, s2
	s_cselect_b32 s2, s66, s68
	s_cselect_b32 s41, s0, s40
	s_cselect_b32 s40, s36, s3
	s_cselect_b32 s3, s65, s69
	v_lshl_add_u64 v[204:205], s[38:39], 0, v[138:139]
	s_add_i32 m0, s29, 0xc000
	ds_read_b128 v[180:183], v146
	ds_read_b128 v[184:187], v146 offset:1024
	ds_read_b128 v[188:191], v146 offset:2048
	ds_read_b128 v[192:195], v146 offset:3072
	ds_read_b128 v[196:199], v146 offset:4096
	ds_read_b128 v[200:203], v146 offset:5120
	ds_read_b128 v[208:211], v146 offset:6144
	ds_read_b128 v[212:215], v146 offset:7168
	global_load_lds_dwordx4 v[204:205], off
	v_lshl_add_u64 v[204:205], s[38:39], 0, v[140:141]
	s_add_i32 m0, s29, 0xe000
	s_nop 0
	global_load_lds_dwordx4 v[204:205], off
	s_waitcnt vmcnt(8)
	s_waitcnt lgkmcnt(0)
	s_barrier
	s_setprio 1
	s_waitcnt lgkmcnt(0)
	v_mfma_f32_16x16x32_bf16 v[126:129], v[148:151], v[180:183], 0
	v_mfma_f32_16x16x32_bf16 v[122:125], v[156:159], v[180:183], 0
	v_mfma_f32_16x16x32_bf16 v[110:113], v[148:151], v[188:191], 0
	v_mfma_f32_16x16x32_bf16 v[102:105], v[156:159], v[188:191], 0
	v_mfma_f32_16x16x32_bf16 v[94:97], v[148:151], v[196:199], 0
	v_mfma_f32_16x16x32_bf16 v[86:89], v[156:159], v[196:199], 0
	v_mfma_f32_16x16x32_bf16 v[78:81], v[148:151], v[208:211], 0
	v_mfma_f32_16x16x32_bf16 v[70:73], v[156:159], v[208:211], 0
	v_mfma_f32_16x16x32_bf16 v[126:129], v[152:155], v[184:187], v[126:129]
	v_mfma_f32_16x16x32_bf16 v[122:125], v[160:163], v[184:187], v[122:125]
	v_mfma_f32_16x16x32_bf16 v[110:113], v[152:155], v[192:195], v[110:113]
	v_mfma_f32_16x16x32_bf16 v[102:105], v[160:163], v[192:195], v[102:105]
	v_mfma_f32_16x16x32_bf16 v[94:97], v[152:155], v[200:203], v[94:97]
	v_mfma_f32_16x16x32_bf16 v[86:89], v[160:163], v[200:203], v[86:89]
	v_mfma_f32_16x16x32_bf16 v[78:81], v[152:155], v[212:215], v[78:81]
	v_mfma_f32_16x16x32_bf16 v[70:73], v[160:163], v[212:215], v[70:73]
	s_setprio 0
	s_setprio 1
	v_mfma_f32_16x16x32_bf16 v[118:121], v[164:167], v[180:183], 0
	v_mfma_f32_16x16x32_bf16 v[114:117], v[172:175], v[180:183], 0
	v_mfma_f32_16x16x32_bf16 v[106:109], v[164:167], v[188:191], 0
	v_mfma_f32_16x16x32_bf16 v[98:101], v[172:175], v[188:191], 0
	v_mfma_f32_16x16x32_bf16 v[90:93], v[164:167], v[196:199], 0
	v_mfma_f32_16x16x32_bf16 v[82:85], v[172:175], v[196:199], 0
	v_mfma_f32_16x16x32_bf16 v[74:77], v[164:167], v[208:211], 0
	v_mfma_f32_16x16x32_bf16 v[66:69], v[172:175], v[208:211], 0
	v_mfma_f32_16x16x32_bf16 v[118:121], v[168:171], v[184:187], v[118:121]
	v_mfma_f32_16x16x32_bf16 v[114:117], v[176:179], v[184:187], v[114:117]
	v_mfma_f32_16x16x32_bf16 v[106:109], v[168:171], v[192:195], v[106:109]
	v_mfma_f32_16x16x32_bf16 v[98:101], v[176:179], v[192:195], v[98:101]
	v_mfma_f32_16x16x32_bf16 v[90:93], v[168:171], v[200:203], v[90:93]
	v_mfma_f32_16x16x32_bf16 v[82:85], v[176:179], v[200:203], v[82:85]
	v_mfma_f32_16x16x32_bf16 v[74:77], v[168:171], v[212:215], v[74:77]
	v_mfma_f32_16x16x32_bf16 v[66:69], v[176:179], v[212:215], v[66:69]
	s_setprio 0
	s_barrier
	s_add_i32 s73, s52, s33
	v_lshl_add_u64 v[204:205], s[2:3], 0, v[132:133]
	s_mov_b32 m0, s73
	ds_read_b128 v[180:183], v146 offset:16384
	ds_read_b128 v[184:187], v146 offset:17408
	ds_read_b128 v[188:191], v146 offset:18432
	ds_read_b128 v[192:195], v146 offset:19456
	ds_read_b128 v[196:199], v146 offset:20480
	ds_read_b128 v[200:203], v146 offset:21504
	ds_read_b128 v[208:211], v146 offset:22528
	ds_read_b128 v[212:215], v146 offset:23552
	global_load_lds_dwordx4 v[204:205], off
	s_add_i32 m0, s73, 0x2000
	s_add_u32 s74, s2, 0x80000
	v_lshl_add_u64 v[216:217], s[2:3], 0, v[136:137]
	s_addc_u32 s75, s3, 0
	s_add_i32 s73, s53, s33
	global_load_lds_dwordx4 v[216:217], off
	v_lshl_add_u64 v[218:219], s[74:75], 0, v[132:133]
	s_mov_b32 m0, s73
	v_lshl_add_u64 v[220:221], s[40:41], 0, v[134:135]
	global_load_lds_dwordx4 v[218:219], off
	v_lshl_add_u64 v[218:219], s[74:75], 0, v[136:137]
	s_add_i32 m0, s73, 0x2000
	s_nop 0
	global_load_lds_dwordx4 v[218:219], off
	v_lshl_add_u64 v[218:219], s[40:41], 0, v[130:131]
	s_mov_b32 m0, s29
	s_nop 0
	global_load_lds_dwordx4 v[218:219], off
	s_mov_b32 m0, s35
	s_nop 0
	global_load_lds_dwordx4 v[220:221], off
	s_waitcnt vmcnt(8)
	s_waitcnt lgkmcnt(0)
	s_barrier
	s_setprio 1
	s_waitcnt lgkmcnt(0)
	v_mfma_f32_16x16x32_bf16 v[62:65], v[148:151], v[180:183], 0
	v_mfma_f32_16x16x32_bf16 v[54:57], v[156:159], v[180:183], 0
	v_mfma_f32_16x16x32_bf16 v[46:49], v[148:151], v[188:191], 0
	v_mfma_f32_16x16x32_bf16 v[38:41], v[156:159], v[188:191], 0
	v_mfma_f32_16x16x32_bf16 v[30:33], v[148:151], v[196:199], 0
	v_mfma_f32_16x16x32_bf16 v[22:25], v[156:159], v[196:199], 0
	v_mfma_f32_16x16x32_bf16 v[14:17], v[148:151], v[208:211], 0
	v_mfma_f32_16x16x32_bf16 v[6:9], v[156:159], v[208:211], 0
	v_mfma_f32_16x16x32_bf16 v[62:65], v[152:155], v[184:187], v[62:65]
	v_mfma_f32_16x16x32_bf16 v[54:57], v[160:163], v[184:187], v[54:57]
	v_mfma_f32_16x16x32_bf16 v[46:49], v[152:155], v[192:195], v[46:49]
	v_mfma_f32_16x16x32_bf16 v[38:41], v[160:163], v[192:195], v[38:41]
	v_mfma_f32_16x16x32_bf16 v[30:33], v[152:155], v[200:203], v[30:33]
	v_mfma_f32_16x16x32_bf16 v[22:25], v[160:163], v[200:203], v[22:25]
	v_mfma_f32_16x16x32_bf16 v[14:17], v[152:155], v[212:215], v[14:17]
	v_mfma_f32_16x16x32_bf16 v[6:9], v[160:163], v[212:215], v[6:9]
	s_setprio 0
	s_setprio 1
	v_mfma_f32_16x16x32_bf16 v[58:61], v[164:167], v[180:183], 0
	v_mfma_f32_16x16x32_bf16 v[50:53], v[172:175], v[180:183], 0
	v_mfma_f32_16x16x32_bf16 v[42:45], v[164:167], v[188:191], 0
	v_mfma_f32_16x16x32_bf16 v[34:37], v[172:175], v[188:191], 0
	v_mfma_f32_16x16x32_bf16 v[26:29], v[164:167], v[196:199], 0
	v_mfma_f32_16x16x32_bf16 v[18:21], v[172:175], v[196:199], 0
	v_mfma_f32_16x16x32_bf16 v[10:13], v[164:167], v[208:211], 0
	v_mfma_f32_16x16x32_bf16 v[2:5], v[172:175], v[208:211], 0
	v_mfma_f32_16x16x32_bf16 v[58:61], v[168:171], v[184:187], v[58:61]
	v_mfma_f32_16x16x32_bf16 v[50:53], v[176:179], v[184:187], v[50:53]
	v_mfma_f32_16x16x32_bf16 v[42:45], v[168:171], v[192:195], v[42:45]
	v_mfma_f32_16x16x32_bf16 v[34:37], v[176:179], v[192:195], v[34:37]
	v_mfma_f32_16x16x32_bf16 v[26:29], v[168:171], v[200:203], v[26:29]
	v_mfma_f32_16x16x32_bf16 v[18:21], v[176:179], v[200:203], v[18:21]
	v_mfma_f32_16x16x32_bf16 v[10:13], v[168:171], v[212:215], v[10:13]
	v_mfma_f32_16x16x32_bf16 v[2:5], v[176:179], v[212:215], v[2:5]
	s_setprio 0
	s_barrier
	s_add_i32 s73, 0, 0x18000
	v_add_u32_e32 v147, s73, v142
	s_add_i32 s74, 0, 0x1c000
	ds_read_b128 v[148:151], v147
	ds_read_b128 v[152:155], v147 offset:1024
	ds_read_b128 v[156:159], v147 offset:2048
	ds_read_b128 v[160:163], v147 offset:3072
	v_add_u32_e32 v147, s74, v142
	ds_read_b128 v[164:167], v147
	ds_read_b128 v[168:171], v147 offset:1024
	ds_read_b128 v[172:175], v147 offset:2048
	ds_read_b128 v[176:179], v147 offset:3072
	s_add_u32 s40, s40, 0x80000
	s_addc_u32 s41, s41, 0
	s_mov_b32 m0, s43
	v_lshl_add_u64 v[222:223], s[40:41], 0, v[130:131]
	ds_read_b128 v[180:183], v146 offset:32768
	ds_read_b128 v[184:187], v146 offset:33792
	ds_read_b128 v[188:191], v146 offset:34816
	ds_read_b128 v[192:195], v146 offset:35840
	ds_read_b128 v[196:199], v146 offset:36864
	ds_read_b128 v[200:203], v146 offset:37888
	ds_read_b128 v[208:211], v146 offset:38912
	ds_read_b128 v[212:215], v146 offset:39936
	global_load_lds_dwordx4 v[222:223], off
	v_lshl_add_u64 v[222:223], s[40:41], 0, v[134:135]
	s_mov_b32 m0, s44
	s_nop 0
	global_load_lds_dwordx4 v[222:223], off
	s_waitcnt vmcnt(8)
	s_waitcnt lgkmcnt(0)
	s_barrier
	s_setprio 1
	s_waitcnt lgkmcnt(0)
	v_mfma_f32_16x16x32_bf16 v[126:129], v[148:151], v[180:183], v[126:129]
	v_mfma_f32_16x16x32_bf16 v[122:125], v[156:159], v[180:183], v[122:125]
	v_mfma_f32_16x16x32_bf16 v[110:113], v[148:151], v[188:191], v[110:113]
	v_mfma_f32_16x16x32_bf16 v[102:105], v[156:159], v[188:191], v[102:105]
	v_mfma_f32_16x16x32_bf16 v[94:97], v[148:151], v[196:199], v[94:97]
	v_mfma_f32_16x16x32_bf16 v[86:89], v[156:159], v[196:199], v[86:89]
	v_mfma_f32_16x16x32_bf16 v[78:81], v[148:151], v[208:211], v[78:81]
	v_mfma_f32_16x16x32_bf16 v[70:73], v[156:159], v[208:211], v[70:73]
	v_mfma_f32_16x16x32_bf16 v[126:129], v[152:155], v[184:187], v[126:129]
	v_mfma_f32_16x16x32_bf16 v[122:125], v[160:163], v[184:187], v[122:125]
	v_mfma_f32_16x16x32_bf16 v[110:113], v[152:155], v[192:195], v[110:113]
	v_mfma_f32_16x16x32_bf16 v[102:105], v[160:163], v[192:195], v[102:105]
	v_mfma_f32_16x16x32_bf16 v[94:97], v[152:155], v[200:203], v[94:97]
	v_mfma_f32_16x16x32_bf16 v[86:89], v[160:163], v[200:203], v[86:89]
	v_mfma_f32_16x16x32_bf16 v[78:81], v[152:155], v[212:215], v[78:81]
	v_mfma_f32_16x16x32_bf16 v[70:73], v[160:163], v[212:215], v[70:73]
	s_setprio 0
	s_setprio 1
	v_mfma_f32_16x16x32_bf16 v[118:121], v[164:167], v[180:183], v[118:121]
	v_mfma_f32_16x16x32_bf16 v[114:117], v[172:175], v[180:183], v[114:117]
	v_mfma_f32_16x16x32_bf16 v[106:109], v[164:167], v[188:191], v[106:109]
	v_mfma_f32_16x16x32_bf16 v[98:101], v[172:175], v[188:191], v[98:101]
	v_mfma_f32_16x16x32_bf16 v[90:93], v[164:167], v[196:199], v[90:93]
	v_mfma_f32_16x16x32_bf16 v[82:85], v[172:175], v[196:199], v[82:85]
	v_mfma_f32_16x16x32_bf16 v[74:77], v[164:167], v[208:211], v[74:77]
	v_mfma_f32_16x16x32_bf16 v[66:69], v[172:175], v[208:211], v[66:69]
	v_mfma_f32_16x16x32_bf16 v[118:121], v[168:171], v[184:187], v[118:121]
	v_mfma_f32_16x16x32_bf16 v[114:117], v[176:179], v[184:187], v[114:117]
	v_mfma_f32_16x16x32_bf16 v[106:109], v[168:171], v[192:195], v[106:109]
	v_mfma_f32_16x16x32_bf16 v[98:101], v[176:179], v[192:195], v[98:101]
	v_mfma_f32_16x16x32_bf16 v[90:93], v[168:171], v[200:203], v[90:93]
	v_mfma_f32_16x16x32_bf16 v[82:85], v[176:179], v[200:203], v[82:85]
	v_mfma_f32_16x16x32_bf16 v[74:77], v[168:171], v[212:215], v[74:77]
	v_mfma_f32_16x16x32_bf16 v[66:69], v[176:179], v[212:215], v[66:69]
	s_setprio 0
	s_barrier
	s_add_i32 s40, s73, s33
	v_lshl_add_u64 v[204:205], v[204:205], 0, s[16:17]
	s_mov_b32 m0, s40
	ds_read_b128 v[180:183], v146 offset:49152
	ds_read_b128 v[184:187], v146 offset:50176
	ds_read_b128 v[188:191], v146 offset:51200
	ds_read_b128 v[192:195], v146 offset:52224
	ds_read_b128 v[196:199], v146 offset:53248
	ds_read_b128 v[200:203], v146 offset:54272
	ds_read_b128 v[208:211], v146 offset:55296
	ds_read_b128 v[212:215], v146 offset:56320
	global_load_lds_dwordx4 v[204:205], off
	s_add_i32 m0, s40, 0x2000
	s_add_u32 s2, s2, 0x80080
	v_lshl_add_u64 v[204:205], v[216:217], 0, s[16:17]
	s_addc_u32 s3, s3, 0
	s_add_i32 s40, s74, s33
	global_load_lds_dwordx4 v[204:205], off
	v_lshl_add_u64 v[204:205], s[2:3], 0, v[132:133]
	s_mov_b32 m0, s40
	s_nop 0
	global_load_lds_dwordx4 v[204:205], off
	v_lshl_add_u64 v[204:205], s[2:3], 0, v[136:137]
	s_add_i32 m0, s40, 0x2000
	s_nop 0
	global_load_lds_dwordx4 v[204:205], off
	v_lshl_add_u64 v[204:205], v[218:219], 0, s[16:17]
	s_mov_b32 m0, s46
	s_nop 0
	global_load_lds_dwordx4 v[204:205], off
	v_lshl_add_u64 v[204:205], v[220:221], 0, s[16:17]
	s_mov_b32 m0, s47
	s_nop 0
	global_load_lds_dwordx4 v[204:205], off
	s_waitcnt vmcnt(8)
	s_waitcnt lgkmcnt(0)
	s_barrier
	s_setprio 1
	s_waitcnt lgkmcnt(0)
	v_mfma_f32_16x16x32_bf16 v[62:65], v[148:151], v[180:183], v[62:65]
	v_mfma_f32_16x16x32_bf16 v[54:57], v[156:159], v[180:183], v[54:57]
	v_mfma_f32_16x16x32_bf16 v[46:49], v[148:151], v[188:191], v[46:49]
	v_mfma_f32_16x16x32_bf16 v[38:41], v[156:159], v[188:191], v[38:41]
	v_mfma_f32_16x16x32_bf16 v[30:33], v[148:151], v[196:199], v[30:33]
	v_mfma_f32_16x16x32_bf16 v[22:25], v[156:159], v[196:199], v[22:25]
	v_mfma_f32_16x16x32_bf16 v[14:17], v[148:151], v[208:211], v[14:17]
	v_mfma_f32_16x16x32_bf16 v[6:9], v[156:159], v[208:211], v[6:9]
	v_mfma_f32_16x16x32_bf16 v[62:65], v[152:155], v[184:187], v[62:65]
	v_mfma_f32_16x16x32_bf16 v[54:57], v[160:163], v[184:187], v[54:57]
	v_mfma_f32_16x16x32_bf16 v[46:49], v[152:155], v[192:195], v[46:49]
	v_mfma_f32_16x16x32_bf16 v[38:41], v[160:163], v[192:195], v[38:41]
	v_mfma_f32_16x16x32_bf16 v[30:33], v[152:155], v[200:203], v[30:33]
	v_mfma_f32_16x16x32_bf16 v[22:25], v[160:163], v[200:203], v[22:25]
	v_mfma_f32_16x16x32_bf16 v[14:17], v[152:155], v[212:215], v[14:17]
	v_mfma_f32_16x16x32_bf16 v[6:9], v[160:163], v[212:215], v[6:9]
	s_setprio 0
	s_setprio 1
	v_mfma_f32_16x16x32_bf16 v[58:61], v[164:167], v[180:183], v[58:61]
	v_mfma_f32_16x16x32_bf16 v[50:53], v[172:175], v[180:183], v[50:53]
	v_mfma_f32_16x16x32_bf16 v[42:45], v[164:167], v[188:191], v[42:45]
	v_mfma_f32_16x16x32_bf16 v[34:37], v[172:175], v[188:191], v[34:37]
	v_mfma_f32_16x16x32_bf16 v[26:29], v[164:167], v[196:199], v[26:29]
	v_mfma_f32_16x16x32_bf16 v[18:21], v[172:175], v[196:199], v[18:21]
	v_mfma_f32_16x16x32_bf16 v[10:13], v[164:167], v[208:211], v[10:13]
	v_mfma_f32_16x16x32_bf16 v[2:5], v[172:175], v[208:211], v[2:5]
	v_mfma_f32_16x16x32_bf16 v[58:61], v[168:171], v[184:187], v[58:61]
	v_mfma_f32_16x16x32_bf16 v[50:53], v[176:179], v[184:187], v[50:53]
	v_mfma_f32_16x16x32_bf16 v[42:45], v[168:171], v[192:195], v[42:45]
	v_mfma_f32_16x16x32_bf16 v[34:37], v[176:179], v[192:195], v[34:37]
	v_mfma_f32_16x16x32_bf16 v[26:29], v[168:171], v[200:203], v[26:29]
	v_mfma_f32_16x16x32_bf16 v[18:21], v[176:179], v[200:203], v[18:21]
	v_mfma_f32_16x16x32_bf16 v[10:13], v[168:171], v[212:215], v[10:13]
	v_mfma_f32_16x16x32_bf16 v[2:5], v[176:179], v[212:215], v[2:5]
	s_setprio 0
	s_barrier
	s_add_u32 s38, s38, 0x100
	s_addc_u32 s39, s39, 0
	s_add_u32 s68, s68, 0x100
	s_addc_u32 s69, s69, 0
	s_cmp_ge_i32 s72, s37
	s_mov_b32 s2, s72
	s_cbranch_scc1 .Lkpeel_exit_2

.Lkpeel_exit_2:
	v_readlane_b32 s66, v248, 30
	v_readlane_b32 s67, v248, 31
	s_and_b64 vcc, exec, s[18:19]
	s_cbranch_vccz .LBB0_529

.LBB0_632:
	s_lshl_b32 s11, s26, 20
	s_and_b32 s11, s11, 0xff00000
	v_readlane_b32 s46, v248, 20
	v_readlane_b32 s47, v248, 21
	s_add_u32 s11, s46, s11
	v_cmp_gt_i64_e64 s[0:1], s[26:27], -1
	s_addc_u32 s16, s47, 0
	s_lshr_b32 s27, s26, 13
	s_and_b32 s27, s27, 0x7ff80
	s_add_u32 s76, s11, s27
	s_addc_u32 s77, s16, 0
	s_lshl_b32 s11, s26, 12
	s_and_b32 s11, s11, 0xff00000
	s_add_u32 s11, s60, s11
	s_addc_u32 s16, s61, 0
	s_add_u32 s78, s11, s27
	s_addc_u32 s79, s16, 0
	s_cmp_lt_i32 s17, 1
	s_cbranch_scc1 .LBB0_640
	s_and_b64 s[26:27], s[0:1], exec
	s_cselect_b32 s11, s77, s19
	s_cselect_b32 s16, s76, s18
	s_cselect_b32 s46, s79, s3
	s_cselect_b32 s47, s78, s2
	s_add_i32 s50, s17, -2
	s_add_u32 s18, s18, 0x80080
	s_addc_u32 s19, s19, 0
	s_add_u32 s51, s2, 0x100
	s_addc_u32 s52, s3, 0
	s_mov_b32 s2, 0
	ds_read_b128 v[130:133], v197
	ds_read_b128 v[134:137], v197 offset:1024
	ds_read_b128 v[138:141], v197 offset:2048
	ds_read_b128 v[142:145], v197 offset:3072
	ds_read_b128 v[146:149], v198
	ds_read_b128 v[150:153], v198 offset:1024
	ds_read_b128 v[154:157], v198 offset:2048
	ds_read_b128 v[170:173], v198 offset:3072
	s_add_i32 s53, s2, 2
	s_add_u32 s3, s18, 0xfff80080
	s_addc_u32 s26, s19, -1
	s_cmp_eq_u32 s50, s2
	s_cselect_b32 s2, s47, s51
	s_cselect_b32 s27, s11, s26
	s_cselect_b32 s26, s16, s3
	s_cselect_b32 s3, s46, s52
	v_lshl_add_u64 v[204:205], s[18:19], 0, v[166:167]
	s_add_i32 m0, s13, 0xc000
	ds_read_b128 v[174:177], v199
	ds_read_b128 v[178:181], v199 offset:1024
	ds_read_b128 v[182:185], v199 offset:2048
	ds_read_b128 v[186:189], v199 offset:3072
	ds_read_b128 v[190:193], v199 offset:4096
	ds_read_b128 v[200:203], v199 offset:5120
	ds_read_b128 v[208:211], v199 offset:6144
	ds_read_b128 v[212:215], v199 offset:7168
	global_load_lds_dwordx4 v[204:205], off
	v_lshl_add_u64 v[204:205], s[18:19], 0, v[168:169]
	s_add_i32 m0, s13, 0xe000
	s_nop 0
	global_load_lds_dwordx4 v[204:205], off
	s_waitcnt vmcnt(8)
	s_waitcnt lgkmcnt(0)
	s_barrier
	s_setprio 1
	s_waitcnt lgkmcnt(0)
	v_mfma_f32_16x16x32_bf16 v[122:125], v[130:133], v[174:177], 0
	v_mfma_f32_16x16x32_bf16 v[114:117], v[138:141], v[174:177], 0
	v_mfma_f32_16x16x32_bf16 v[106:109], v[130:133], v[182:185], 0
	v_mfma_f32_16x16x32_bf16 v[98:101], v[138:141], v[182:185], 0
	v_mfma_f32_16x16x32_bf16 v[90:93], v[130:133], v[190:193], 0
	v_mfma_f32_16x16x32_bf16 v[82:85], v[138:141], v[190:193], 0
	v_mfma_f32_16x16x32_bf16 v[74:77], v[130:133], v[208:211], 0
	v_mfma_f32_16x16x32_bf16 v[66:69], v[138:141], v[208:211], 0
	v_mfma_f32_16x16x32_bf16 v[122:125], v[134:137], v[178:181], v[122:125]
	v_mfma_f32_16x16x32_bf16 v[114:117], v[142:145], v[178:181], v[114:117]
	v_mfma_f32_16x16x32_bf16 v[106:109], v[134:137], v[186:189], v[106:109]
	v_mfma_f32_16x16x32_bf16 v[98:101], v[142:145], v[186:189], v[98:101]
	v_mfma_f32_16x16x32_bf16 v[90:93], v[134:137], v[200:203], v[90:93]
	v_mfma_f32_16x16x32_bf16 v[82:85], v[142:145], v[200:203], v[82:85]
	v_mfma_f32_16x16x32_bf16 v[74:77], v[134:137], v[212:215], v[74:77]
	v_mfma_f32_16x16x32_bf16 v[66:69], v[142:145], v[212:215], v[66:69]
	s_setprio 0
	s_setprio 1
	v_mfma_f32_16x16x32_bf16 v[126:129], v[146:149], v[174:177], 0
	v_mfma_f32_16x16x32_bf16 v[118:121], v[154:157], v[174:177], 0
	v_mfma_f32_16x16x32_bf16 v[110:113], v[146:149], v[182:185], 0
	v_mfma_f32_16x16x32_bf16 v[102:105], v[154:157], v[182:185], 0
	v_mfma_f32_16x16x32_bf16 v[94:97], v[146:149], v[190:193], 0
	v_mfma_f32_16x16x32_bf16 v[86:89], v[154:157], v[190:193], 0
	v_mfma_f32_16x16x32_bf16 v[78:81], v[146:149], v[208:211], 0
	v_mfma_f32_16x16x32_bf16 v[70:73], v[154:157], v[208:211], 0
	v_mfma_f32_16x16x32_bf16 v[126:129], v[150:153], v[178:181], v[126:129]
	v_mfma_f32_16x16x32_bf16 v[118:121], v[170:173], v[178:181], v[118:121]
	v_mfma_f32_16x16x32_bf16 v[110:113], v[150:153], v[186:189], v[110:113]
	v_mfma_f32_16x16x32_bf16 v[102:105], v[170:173], v[186:189], v[102:105]
	v_mfma_f32_16x16x32_bf16 v[94:97], v[150:153], v[200:203], v[94:97]
	v_mfma_f32_16x16x32_bf16 v[86:89], v[170:173], v[200:203], v[86:89]
	v_mfma_f32_16x16x32_bf16 v[78:81], v[150:153], v[212:215], v[78:81]
	v_mfma_f32_16x16x32_bf16 v[70:73], v[170:173], v[212:215], v[70:73]
	s_setprio 0
	s_barrier
	s_add_i32 s64, s44, s35
	v_lshl_add_u64 v[204:205], s[2:3], 0, v[160:161]
	s_mov_b32 m0, s64
	ds_read_b128 v[174:177], v199 offset:16384
	ds_read_b128 v[178:181], v199 offset:17408
	ds_read_b128 v[182:185], v199 offset:18432
	ds_read_b128 v[186:189], v199 offset:19456
	ds_read_b128 v[190:193], v199 offset:20480
	ds_read_b128 v[200:203], v199 offset:21504
	ds_read_b128 v[208:211], v199 offset:22528
	ds_read_b128 v[212:215], v199 offset:23552
	global_load_lds_dwordx4 v[204:205], off
	s_add_i32 m0, s64, 0x2000
	s_add_u32 s80, s2, 0x80000
	v_lshl_add_u64 v[216:217], s[2:3], 0, v[164:165]
	s_addc_u32 s81, s3, 0
	s_add_i32 s64, s45, s35
	global_load_lds_dwordx4 v[216:217], off
	v_lshl_add_u64 v[218:219], s[80:81], 0, v[160:161]
	s_mov_b32 m0, s64
	v_lshl_add_u64 v[220:221], s[26:27], 0, v[162:163]
	global_load_lds_dwordx4 v[218:219], off
	v_lshl_add_u64 v[218:219], s[80:81], 0, v[164:165]
	s_add_i32 m0, s64, 0x2000
	s_nop 0
	global_load_lds_dwordx4 v[218:219], off
	v_lshl_add_u64 v[218:219], s[26:27], 0, v[158:159]
	s_mov_b32 m0, s13
	s_nop 0
	global_load_lds_dwordx4 v[218:219], off
	s_mov_b32 m0, s36
	s_nop 0
	global_load_lds_dwordx4 v[220:221], off
	s_waitcnt vmcnt(8)
	s_waitcnt lgkmcnt(0)
	s_barrier
	s_setprio 1
	s_waitcnt lgkmcnt(0)
	v_mfma_f32_16x16x32_bf16 v[58:61], v[130:133], v[174:177], 0
	v_mfma_f32_16x16x32_bf16 v[50:53], v[138:141], v[174:177], 0
	v_mfma_f32_16x16x32_bf16 v[42:45], v[130:133], v[182:185], 0
	v_mfma_f32_16x16x32_bf16 v[34:37], v[138:141], v[182:185], 0
	v_mfma_f32_16x16x32_bf16 v[26:29], v[130:133], v[190:193], 0
	v_mfma_f32_16x16x32_bf16 v[18:21], v[138:141], v[190:193], 0
	v_mfma_f32_16x16x32_bf16 v[10:13], v[130:133], v[208:211], 0
	v_mfma_f32_16x16x32_bf16 v[2:5], v[138:141], v[208:211], 0
	v_mfma_f32_16x16x32_bf16 v[58:61], v[134:137], v[178:181], v[58:61]
	v_mfma_f32_16x16x32_bf16 v[50:53], v[142:145], v[178:181], v[50:53]
	v_mfma_f32_16x16x32_bf16 v[42:45], v[134:137], v[186:189], v[42:45]
	v_mfma_f32_16x16x32_bf16 v[34:37], v[142:145], v[186:189], v[34:37]
	v_mfma_f32_16x16x32_bf16 v[26:29], v[134:137], v[200:203], v[26:29]
	v_mfma_f32_16x16x32_bf16 v[18:21], v[142:145], v[200:203], v[18:21]
	v_mfma_f32_16x16x32_bf16 v[10:13], v[134:137], v[212:215], v[10:13]
	v_mfma_f32_16x16x32_bf16 v[2:5], v[142:145], v[212:215], v[2:5]
	s_setprio 0
	s_setprio 1
	v_mfma_f32_16x16x32_bf16 v[62:65], v[146:149], v[174:177], 0
	v_mfma_f32_16x16x32_bf16 v[54:57], v[154:157], v[174:177], 0
	v_mfma_f32_16x16x32_bf16 v[46:49], v[146:149], v[182:185], 0
	v_mfma_f32_16x16x32_bf16 v[38:41], v[154:157], v[182:185], 0
	v_mfma_f32_16x16x32_bf16 v[30:33], v[146:149], v[190:193], 0
	v_mfma_f32_16x16x32_bf16 v[22:25], v[154:157], v[190:193], 0
	v_mfma_f32_16x16x32_bf16 v[14:17], v[146:149], v[208:211], 0
	v_mfma_f32_16x16x32_bf16 v[6:9], v[154:157], v[208:211], 0
	v_mfma_f32_16x16x32_bf16 v[62:65], v[150:153], v[178:181], v[62:65]
	v_mfma_f32_16x16x32_bf16 v[54:57], v[170:173], v[178:181], v[54:57]
	v_mfma_f32_16x16x32_bf16 v[46:49], v[150:153], v[186:189], v[46:49]
	v_mfma_f32_16x16x32_bf16 v[38:41], v[170:173], v[186:189], v[38:41]
	v_mfma_f32_16x16x32_bf16 v[30:33], v[150:153], v[200:203], v[30:33]
	v_mfma_f32_16x16x32_bf16 v[22:25], v[170:173], v[200:203], v[22:25]
	v_mfma_f32_16x16x32_bf16 v[14:17], v[150:153], v[212:215], v[14:17]
	v_mfma_f32_16x16x32_bf16 v[6:9], v[170:173], v[212:215], v[6:9]
	s_setprio 0
	s_barrier
	s_add_i32 s64, 0, 0x18000
	s_add_i32 s75, 0, 0x1c000
	v_add_u32_e32 v142, s64, v194
	v_add_u32_e32 v170, s75, v194
	ds_read_b128 v[130:133], v142
	ds_read_b128 v[134:137], v142 offset:1024
	ds_read_b128 v[138:141], v142 offset:2048
	ds_read_b128 v[142:145], v142 offset:3072
	ds_read_b128 v[146:149], v170
	ds_read_b128 v[150:153], v170 offset:1024
	ds_read_b128 v[154:157], v170 offset:2048
	ds_read_b128 v[170:173], v170 offset:3072
	s_add_u32 s26, s26, 0x80000
	s_addc_u32 s27, s27, 0
	s_mov_b32 m0, s37
	v_lshl_add_u64 v[222:223], s[26:27], 0, v[158:159]
	ds_read_b128 v[174:177], v199 offset:32768
	ds_read_b128 v[178:181], v199 offset:33792
	ds_read_b128 v[182:185], v199 offset:34816
	ds_read_b128 v[186:189], v199 offset:35840
	ds_read_b128 v[190:193], v199 offset:36864
	ds_read_b128 v[200:203], v199 offset:37888
	ds_read_b128 v[208:211], v199 offset:38912
	ds_read_b128 v[212:215], v199 offset:39936
	global_load_lds_dwordx4 v[222:223], off
	v_lshl_add_u64 v[222:223], s[26:27], 0, v[162:163]
	s_mov_b32 m0, s38
	s_nop 0
	global_load_lds_dwordx4 v[222:223], off
	s_waitcnt vmcnt(8)
	s_waitcnt lgkmcnt(0)
	s_barrier
	s_setprio 1
	s_waitcnt lgkmcnt(0)
	v_mfma_f32_16x16x32_bf16 v[122:125], v[130:133], v[174:177], v[122:125]
	v_mfma_f32_16x16x32_bf16 v[114:117], v[138:141], v[174:177], v[114:117]
	v_mfma_f32_16x16x32_bf16 v[106:109], v[130:133], v[182:185], v[106:109]
	v_mfma_f32_16x16x32_bf16 v[98:101], v[138:141], v[182:185], v[98:101]
	v_mfma_f32_16x16x32_bf16 v[90:93], v[130:133], v[190:193], v[90:93]
	v_mfma_f32_16x16x32_bf16 v[82:85], v[138:141], v[190:193], v[82:85]
	v_mfma_f32_16x16x32_bf16 v[74:77], v[130:133], v[208:211], v[74:77]
	v_mfma_f32_16x16x32_bf16 v[66:69], v[138:141], v[208:211], v[66:69]
	v_mfma_f32_16x16x32_bf16 v[122:125], v[134:137], v[178:181], v[122:125]
	v_mfma_f32_16x16x32_bf16 v[114:117], v[142:145], v[178:181], v[114:117]
	v_mfma_f32_16x16x32_bf16 v[106:109], v[134:137], v[186:189], v[106:109]
	v_mfma_f32_16x16x32_bf16 v[98:101], v[142:145], v[186:189], v[98:101]
	v_mfma_f32_16x16x32_bf16 v[90:93], v[134:137], v[200:203], v[90:93]
	v_mfma_f32_16x16x32_bf16 v[82:85], v[142:145], v[200:203], v[82:85]
	v_mfma_f32_16x16x32_bf16 v[74:77], v[134:137], v[212:215], v[74:77]
	v_mfma_f32_16x16x32_bf16 v[66:69], v[142:145], v[212:215], v[66:69]
	s_setprio 0
	s_setprio 1
	v_mfma_f32_16x16x32_bf16 v[126:129], v[146:149], v[174:177], v[126:129]
	v_mfma_f32_16x16x32_bf16 v[118:121], v[154:157], v[174:177], v[118:121]
	v_mfma_f32_16x16x32_bf16 v[110:113], v[146:149], v[182:185], v[110:113]
	v_mfma_f32_16x16x32_bf16 v[102:105], v[154:157], v[182:185], v[102:105]
	v_mfma_f32_16x16x32_bf16 v[94:97], v[146:149], v[190:193], v[94:97]
	v_mfma_f32_16x16x32_bf16 v[86:89], v[154:157], v[190:193], v[86:89]
	v_mfma_f32_16x16x32_bf16 v[78:81], v[146:149], v[208:211], v[78:81]
	v_mfma_f32_16x16x32_bf16 v[70:73], v[154:157], v[208:211], v[70:73]
	v_mfma_f32_16x16x32_bf16 v[126:129], v[150:153], v[178:181], v[126:129]
	v_mfma_f32_16x16x32_bf16 v[118:121], v[170:173], v[178:181], v[118:121]
	v_mfma_f32_16x16x32_bf16 v[110:113], v[150:153], v[186:189], v[110:113]
	v_mfma_f32_16x16x32_bf16 v[102:105], v[170:173], v[186:189], v[102:105]
	v_mfma_f32_16x16x32_bf16 v[94:97], v[150:153], v[200:203], v[94:97]
	v_mfma_f32_16x16x32_bf16 v[86:89], v[170:173], v[200:203], v[86:89]
	v_mfma_f32_16x16x32_bf16 v[78:81], v[150:153], v[212:215], v[78:81]
	v_mfma_f32_16x16x32_bf16 v[70:73], v[170:173], v[212:215], v[70:73]
	s_setprio 0
	s_barrier
	s_add_i32 s26, s64, s35
	v_lshl_add_u64 v[204:205], v[204:205], 0, s[68:69]
	s_mov_b32 m0, s26
	ds_read_b128 v[174:177], v199 offset:49152
	ds_read_b128 v[178:181], v199 offset:50176
	ds_read_b128 v[182:185], v199 offset:51200
	ds_read_b128 v[186:189], v199 offset:52224
	ds_read_b128 v[190:193], v199 offset:53248
	ds_read_b128 v[200:203], v199 offset:54272
	ds_read_b128 v[208:211], v199 offset:55296
	ds_read_b128 v[212:215], v199 offset:56320
	global_load_lds_dwordx4 v[204:205], off
	s_add_i32 m0, s26, 0x2000
	s_add_u32 s2, s2, 0x80080
	v_lshl_add_u64 v[204:205], v[216:217], 0, s[68:69]
	s_addc_u32 s3, s3, 0
	s_add_i32 s26, s75, s35
	global_load_lds_dwordx4 v[204:205], off
	v_lshl_add_u64 v[204:205], s[2:3], 0, v[160:161]
	s_mov_b32 m0, s26
	s_nop 0
	global_load_lds_dwordx4 v[204:205], off
	v_lshl_add_u64 v[204:205], s[2:3], 0, v[164:165]
	s_add_i32 m0, s26, 0x2000
	s_nop 0
	global_load_lds_dwordx4 v[204:205], off
	v_lshl_add_u64 v[204:205], v[218:219], 0, s[68:69]
	s_mov_b32 m0, s40
	s_nop 0
	global_load_lds_dwordx4 v[204:205], off
	v_lshl_add_u64 v[204:205], v[220:221], 0, s[68:69]
	s_mov_b32 m0, s41
	s_nop 0
	global_load_lds_dwordx4 v[204:205], off
	s_waitcnt vmcnt(8)
	s_waitcnt lgkmcnt(0)
	s_barrier
	s_setprio 1
	s_waitcnt lgkmcnt(0)
	v_mfma_f32_16x16x32_bf16 v[58:61], v[130:133], v[174:177], v[58:61]
	v_mfma_f32_16x16x32_bf16 v[50:53], v[138:141], v[174:177], v[50:53]
	v_mfma_f32_16x16x32_bf16 v[42:45], v[130:133], v[182:185], v[42:45]
	v_mfma_f32_16x16x32_bf16 v[34:37], v[138:141], v[182:185], v[34:37]
	v_mfma_f32_16x16x32_bf16 v[26:29], v[130:133], v[190:193], v[26:29]
	v_mfma_f32_16x16x32_bf16 v[18:21], v[138:141], v[190:193], v[18:21]
	v_mfma_f32_16x16x32_bf16 v[10:13], v[130:133], v[208:211], v[10:13]
	v_mfma_f32_16x16x32_bf16 v[2:5], v[138:141], v[208:211], v[2:5]
	v_mfma_f32_16x16x32_bf16 v[58:61], v[134:137], v[178:181], v[58:61]
	v_mfma_f32_16x16x32_bf16 v[50:53], v[142:145], v[178:181], v[50:53]
	v_mfma_f32_16x16x32_bf16 v[42:45], v[134:137], v[186:189], v[42:45]
	v_mfma_f32_16x16x32_bf16 v[34:37], v[142:145], v[186:189], v[34:37]
	v_mfma_f32_16x16x32_bf16 v[26:29], v[134:137], v[200:203], v[26:29]
	v_mfma_f32_16x16x32_bf16 v[18:21], v[142:145], v[200:203], v[18:21]
	v_mfma_f32_16x16x32_bf16 v[10:13], v[134:137], v[212:215], v[10:13]
	v_mfma_f32_16x16x32_bf16 v[2:5], v[142:145], v[212:215], v[2:5]
	s_setprio 0
	s_setprio 1
	v_mfma_f32_16x16x32_bf16 v[62:65], v[146:149], v[174:177], v[62:65]
	v_mfma_f32_16x16x32_bf16 v[54:57], v[154:157], v[174:177], v[54:57]
	v_mfma_f32_16x16x32_bf16 v[46:49], v[146:149], v[182:185], v[46:49]
	v_mfma_f32_16x16x32_bf16 v[38:41], v[154:157], v[182:185], v[38:41]
	v_mfma_f32_16x16x32_bf16 v[30:33], v[146:149], v[190:193], v[30:33]
	v_mfma_f32_16x16x32_bf16 v[22:25], v[154:157], v[190:193], v[22:25]
	v_mfma_f32_16x16x32_bf16 v[14:17], v[146:149], v[208:211], v[14:17]
	v_mfma_f32_16x16x32_bf16 v[6:9], v[154:157], v[208:211], v[6:9]
	v_mfma_f32_16x16x32_bf16 v[62:65], v[150:153], v[178:181], v[62:65]
	v_mfma_f32_16x16x32_bf16 v[54:57], v[170:173], v[178:181], v[54:57]
	v_mfma_f32_16x16x32_bf16 v[46:49], v[150:153], v[186:189], v[46:49]
	v_mfma_f32_16x16x32_bf16 v[38:41], v[170:173], v[186:189], v[38:41]
	v_mfma_f32_16x16x32_bf16 v[30:33], v[150:153], v[200:203], v[30:33]
	v_mfma_f32_16x16x32_bf16 v[22:25], v[170:173], v[200:203], v[22:25]
	v_mfma_f32_16x16x32_bf16 v[14:17], v[150:153], v[212:215], v[14:17]
	v_mfma_f32_16x16x32_bf16 v[6:9], v[170:173], v[212:215], v[6:9]
	s_setprio 0
	s_barrier
	s_add_u32 s18, s18, 0x100
	s_addc_u32 s19, s19, 0
	s_add_u32 s51, s51, 0x100
	s_addc_u32 s52, s52, 0
	s_cmp_ge_i32 s53, s17
	s_mov_b32 s2, s53
	s_cbranch_scc1 .Lkpeel_exit_3

.Lkpeel_exit_3:
	s_and_b64 vcc, exec, s[70:71]
	s_cbranch_vccz .LBB0_641

.LBB0_798:
	s_lshl_b32 s0, s26, 21
	s_and_b32 s0, s0, 0x1fe00000
	v_readlane_b32 s22, v248, 22
	v_readlane_b32 s23, v248, 23
	s_add_u32 s0, s22, s0
	s_addc_u32 s23, s23, 0
	s_lshr_b32 s22, s26, 13
	s_and_b32 s24, s22, 0x7ff80
	s_add_u32 s22, s0, s24
	s_addc_u32 s23, s23, 0
	s_lshl_b32 s0, s26, 13
	s_and_b32 s0, s0, 0x1fe00000
	s_add_u32 s0, s82, s0
	s_addc_u32 s25, s83, 0
	s_add_u32 s24, s0, s24
	s_addc_u32 s25, s25, 0
	s_cmp_lt_i32 s35, 1
	v_cmp_gt_i64_e64 s[26:27], s[26:27], -1
	s_cbranch_scc1 .LBB0_820
	s_and_b64 s[38:39], s[26:27], exec
	s_cselect_b32 s0, s23, s37
	s_cselect_b32 s34, s22, s36
	s_cselect_b32 s56, s25, s3
	s_cselect_b32 s57, s24, s2
	s_add_i32 s58, s35, -2
	s_add_u32 s36, s36, 0x100080
	s_addc_u32 s37, s37, 0
	s_add_u32 s59, s2, 0x100
	s_addc_u32 s60, s3, 0
	s_mov_b32 s2, 0
	ds_read_b128 v[148:151], v144
	ds_read_b128 v[152:155], v144 offset:1024
	ds_read_b128 v[156:159], v144 offset:2048
	ds_read_b128 v[160:163], v144 offset:3072
	ds_read_b128 v[164:167], v145
	ds_read_b128 v[168:171], v145 offset:1024
	ds_read_b128 v[172:175], v145 offset:2048
	ds_read_b128 v[176:179], v145 offset:3072
	s_add_i32 s61, s2, 2
	s_add_u32 s3, s36, 0xfff00080
	s_addc_u32 s38, s37, -1
	s_cmp_eq_u32 s58, s2
	s_cselect_b32 s2, s57, s59
	s_cselect_b32 s39, s0, s38
	s_cselect_b32 s38, s34, s3
	s_cselect_b32 s3, s56, s60
	v_lshl_add_u64 v[204:205], s[36:37], 0, v[138:139]
	s_add_i32 m0, s29, 0xc000
	ds_read_b128 v[180:183], v146
	ds_read_b128 v[184:187], v146 offset:1024
	ds_read_b128 v[188:191], v146 offset:2048
	ds_read_b128 v[192:195], v146 offset:3072
	ds_read_b128 v[196:199], v146 offset:4096
	ds_read_b128 v[200:203], v146 offset:5120
	ds_read_b128 v[208:211], v146 offset:6144
	ds_read_b128 v[212:215], v146 offset:7168
	global_load_lds_dwordx4 v[204:205], off
	v_lshl_add_u64 v[204:205], s[36:37], 0, v[140:141]
	s_add_i32 m0, s29, 0xe000
	s_nop 0
	global_load_lds_dwordx4 v[204:205], off
	s_waitcnt vmcnt(8)
	s_waitcnt lgkmcnt(0)
	s_barrier
	s_setprio 1
	s_waitcnt lgkmcnt(0)
	v_mfma_f32_16x16x32_bf16 v[126:129], v[148:151], v[180:183], 0
	v_mfma_f32_16x16x32_bf16 v[122:125], v[156:159], v[180:183], 0
	v_mfma_f32_16x16x32_bf16 v[110:113], v[148:151], v[188:191], 0
	v_mfma_f32_16x16x32_bf16 v[102:105], v[156:159], v[188:191], 0
	v_mfma_f32_16x16x32_bf16 v[94:97], v[148:151], v[196:199], 0
	v_mfma_f32_16x16x32_bf16 v[86:89], v[156:159], v[196:199], 0
	v_mfma_f32_16x16x32_bf16 v[78:81], v[148:151], v[208:211], 0
	v_mfma_f32_16x16x32_bf16 v[70:73], v[156:159], v[208:211], 0
	v_mfma_f32_16x16x32_bf16 v[126:129], v[152:155], v[184:187], v[126:129]
	v_mfma_f32_16x16x32_bf16 v[122:125], v[160:163], v[184:187], v[122:125]
	v_mfma_f32_16x16x32_bf16 v[110:113], v[152:155], v[192:195], v[110:113]
	v_mfma_f32_16x16x32_bf16 v[102:105], v[160:163], v[192:195], v[102:105]
	v_mfma_f32_16x16x32_bf16 v[94:97], v[152:155], v[200:203], v[94:97]
	v_mfma_f32_16x16x32_bf16 v[86:89], v[160:163], v[200:203], v[86:89]
	v_mfma_f32_16x16x32_bf16 v[78:81], v[152:155], v[212:215], v[78:81]
	v_mfma_f32_16x16x32_bf16 v[70:73], v[160:163], v[212:215], v[70:73]
	s_setprio 0
	s_setprio 1
	v_mfma_f32_16x16x32_bf16 v[118:121], v[164:167], v[180:183], 0
	v_mfma_f32_16x16x32_bf16 v[114:117], v[172:175], v[180:183], 0
	v_mfma_f32_16x16x32_bf16 v[106:109], v[164:167], v[188:191], 0
	v_mfma_f32_16x16x32_bf16 v[98:101], v[172:175], v[188:191], 0
	v_mfma_f32_16x16x32_bf16 v[90:93], v[164:167], v[196:199], 0
	v_mfma_f32_16x16x32_bf16 v[82:85], v[172:175], v[196:199], 0
	v_mfma_f32_16x16x32_bf16 v[74:77], v[164:167], v[208:211], 0
	v_mfma_f32_16x16x32_bf16 v[66:69], v[172:175], v[208:211], 0
	v_mfma_f32_16x16x32_bf16 v[118:121], v[168:171], v[184:187], v[118:121]
	v_mfma_f32_16x16x32_bf16 v[114:117], v[176:179], v[184:187], v[114:117]
	v_mfma_f32_16x16x32_bf16 v[106:109], v[168:171], v[192:195], v[106:109]
	v_mfma_f32_16x16x32_bf16 v[98:101], v[176:179], v[192:195], v[98:101]
	v_mfma_f32_16x16x32_bf16 v[90:93], v[168:171], v[200:203], v[90:93]
	v_mfma_f32_16x16x32_bf16 v[82:85], v[176:179], v[200:203], v[82:85]
	v_mfma_f32_16x16x32_bf16 v[74:77], v[168:171], v[212:215], v[74:77]
	v_mfma_f32_16x16x32_bf16 v[66:69], v[176:179], v[212:215], v[66:69]
	s_setprio 0
	s_barrier
	s_add_i32 s64, s50, s33
	v_lshl_add_u64 v[204:205], s[2:3], 0, v[132:133]
	s_mov_b32 m0, s64
	ds_read_b128 v[180:183], v146 offset:16384
	ds_read_b128 v[184:187], v146 offset:17408
	ds_read_b128 v[188:191], v146 offset:18432
	ds_read_b128 v[192:195], v146 offset:19456
	ds_read_b128 v[196:199], v146 offset:20480
	ds_read_b128 v[200:203], v146 offset:21504
	ds_read_b128 v[208:211], v146 offset:22528
	ds_read_b128 v[212:215], v146 offset:23552
	global_load_lds_dwordx4 v[204:205], off
	s_add_i32 m0, s64, 0x2000
	s_add_u32 s64, s2, 0x100000
	v_lshl_add_u64 v[216:217], s[2:3], 0, v[136:137]
	s_addc_u32 s65, s3, 0
	s_add_i32 s66, s51, s33
	global_load_lds_dwordx4 v[216:217], off
	v_lshl_add_u64 v[218:219], s[64:65], 0, v[132:133]
	s_mov_b32 m0, s66
	v_lshl_add_u64 v[220:221], s[38:39], 0, v[134:135]
	global_load_lds_dwordx4 v[218:219], off
	v_lshl_add_u64 v[218:219], s[64:65], 0, v[136:137]
	s_add_i32 m0, s66, 0x2000
	s_nop 0
	global_load_lds_dwordx4 v[218:219], off
	v_lshl_add_u64 v[218:219], s[38:39], 0, v[130:131]
	s_mov_b32 m0, s29
	s_nop 0
	global_load_lds_dwordx4 v[218:219], off
	s_mov_b32 m0, s31
	s_nop 0
	global_load_lds_dwordx4 v[220:221], off
	s_waitcnt vmcnt(8)
	s_waitcnt lgkmcnt(0)
	s_barrier
	s_setprio 1
	s_waitcnt lgkmcnt(0)
	v_mfma_f32_16x16x32_bf16 v[62:65], v[148:151], v[180:183], 0
	v_mfma_f32_16x16x32_bf16 v[54:57], v[156:159], v[180:183], 0
	v_mfma_f32_16x16x32_bf16 v[46:49], v[148:151], v[188:191], 0
	v_mfma_f32_16x16x32_bf16 v[38:41], v[156:159], v[188:191], 0
	v_mfma_f32_16x16x32_bf16 v[30:33], v[148:151], v[196:199], 0
	v_mfma_f32_16x16x32_bf16 v[22:25], v[156:159], v[196:199], 0
	v_mfma_f32_16x16x32_bf16 v[14:17], v[148:151], v[208:211], 0
	v_mfma_f32_16x16x32_bf16 v[6:9], v[156:159], v[208:211], 0
	v_mfma_f32_16x16x32_bf16 v[62:65], v[152:155], v[184:187], v[62:65]
	v_mfma_f32_16x16x32_bf16 v[54:57], v[160:163], v[184:187], v[54:57]
	v_mfma_f32_16x16x32_bf16 v[46:49], v[152:155], v[192:195], v[46:49]
	v_mfma_f32_16x16x32_bf16 v[38:41], v[160:163], v[192:195], v[38:41]
	v_mfma_f32_16x16x32_bf16 v[30:33], v[152:155], v[200:203], v[30:33]
	v_mfma_f32_16x16x32_bf16 v[22:25], v[160:163], v[200:203], v[22:25]
	v_mfma_f32_16x16x32_bf16 v[14:17], v[152:155], v[212:215], v[14:17]
	v_mfma_f32_16x16x32_bf16 v[6:9], v[160:163], v[212:215], v[6:9]
	s_setprio 0
	s_setprio 1
	v_mfma_f32_16x16x32_bf16 v[58:61], v[164:167], v[180:183], 0
	v_mfma_f32_16x16x32_bf16 v[50:53], v[172:175], v[180:183], 0
	v_mfma_f32_16x16x32_bf16 v[42:45], v[164:167], v[188:191], 0
	v_mfma_f32_16x16x32_bf16 v[34:37], v[172:175], v[188:191], 0
	v_mfma_f32_16x16x32_bf16 v[26:29], v[164:167], v[196:199], 0
	v_mfma_f32_16x16x32_bf16 v[18:21], v[172:175], v[196:199], 0
	v_mfma_f32_16x16x32_bf16 v[10:13], v[164:167], v[208:211], 0
	v_mfma_f32_16x16x32_bf16 v[2:5], v[172:175], v[208:211], 0
	v_mfma_f32_16x16x32_bf16 v[58:61], v[168:171], v[184:187], v[58:61]
	v_mfma_f32_16x16x32_bf16 v[50:53], v[176:179], v[184:187], v[50:53]
	v_mfma_f32_16x16x32_bf16 v[42:45], v[168:171], v[192:195], v[42:45]
	v_mfma_f32_16x16x32_bf16 v[34:37], v[176:179], v[192:195], v[34:37]
	v_mfma_f32_16x16x32_bf16 v[26:29], v[168:171], v[200:203], v[26:29]
	v_mfma_f32_16x16x32_bf16 v[18:21], v[176:179], v[200:203], v[18:21]
	v_mfma_f32_16x16x32_bf16 v[10:13], v[168:171], v[212:215], v[10:13]
	v_mfma_f32_16x16x32_bf16 v[2:5], v[176:179], v[212:215], v[2:5]
	s_setprio 0
	s_barrier
	s_add_i32 s64, 0, 0x18000
	v_add_u32_e32 v147, s64, v142
	s_add_i32 s65, 0, 0x1c000
	ds_read_b128 v[148:151], v147
	ds_read_b128 v[152:155], v147 offset:1024
	ds_read_b128 v[156:159], v147 offset:2048
	ds_read_b128 v[160:163], v147 offset:3072
	v_add_u32_e32 v147, s65, v142
	ds_read_b128 v[164:167], v147
	ds_read_b128 v[168:171], v147 offset:1024
	ds_read_b128 v[172:175], v147 offset:2048
	ds_read_b128 v[176:179], v147 offset:3072
	s_add_u32 s38, s38, 0x100000
	s_addc_u32 s39, s39, 0
	s_mov_b32 m0, s41
	v_lshl_add_u64 v[222:223], s[38:39], 0, v[130:131]
	ds_read_b128 v[180:183], v146 offset:32768
	ds_read_b128 v[184:187], v146 offset:33792
	ds_read_b128 v[188:191], v146 offset:34816
	ds_read_b128 v[192:195], v146 offset:35840
	ds_read_b128 v[196:199], v146 offset:36864
	ds_read_b128 v[200:203], v146 offset:37888
	ds_read_b128 v[208:211], v146 offset:38912
	ds_read_b128 v[212:215], v146 offset:39936
	global_load_lds_dwordx4 v[222:223], off
	v_lshl_add_u64 v[222:223], s[38:39], 0, v[134:135]
	s_mov_b32 m0, s42
	s_nop 0
	global_load_lds_dwordx4 v[222:223], off
	s_waitcnt vmcnt(8)
	s_waitcnt lgkmcnt(0)
	s_barrier
	s_setprio 1
	s_waitcnt lgkmcnt(0)
	v_mfma_f32_16x16x32_bf16 v[126:129], v[148:151], v[180:183], v[126:129]
	v_mfma_f32_16x16x32_bf16 v[122:125], v[156:159], v[180:183], v[122:125]
	v_mfma_f32_16x16x32_bf16 v[110:113], v[148:151], v[188:191], v[110:113]
	v_mfma_f32_16x16x32_bf16 v[102:105], v[156:159], v[188:191], v[102:105]
	v_mfma_f32_16x16x32_bf16 v[94:97], v[148:151], v[196:199], v[94:97]
	v_mfma_f32_16x16x32_bf16 v[86:89], v[156:159], v[196:199], v[86:89]
	v_mfma_f32_16x16x32_bf16 v[78:81], v[148:151], v[208:211], v[78:81]
	v_mfma_f32_16x16x32_bf16 v[70:73], v[156:159], v[208:211], v[70:73]
	v_mfma_f32_16x16x32_bf16 v[126:129], v[152:155], v[184:187], v[126:129]
	v_mfma_f32_16x16x32_bf16 v[122:125], v[160:163], v[184:187], v[122:125]
	v_mfma_f32_16x16x32_bf16 v[110:113], v[152:155], v[192:195], v[110:113]
	v_mfma_f32_16x16x32_bf16 v[102:105], v[160:163], v[192:195], v[102:105]
	v_mfma_f32_16x16x32_bf16 v[94:97], v[152:155], v[200:203], v[94:97]
	v_mfma_f32_16x16x32_bf16 v[86:89], v[160:163], v[200:203], v[86:89]
	v_mfma_f32_16x16x32_bf16 v[78:81], v[152:155], v[212:215], v[78:81]
	v_mfma_f32_16x16x32_bf16 v[70:73], v[160:163], v[212:215], v[70:73]
	s_setprio 0
	s_setprio 1
	v_mfma_f32_16x16x32_bf16 v[118:121], v[164:167], v[180:183], v[118:121]
	v_mfma_f32_16x16x32_bf16 v[114:117], v[172:175], v[180:183], v[114:117]
	v_mfma_f32_16x16x32_bf16 v[106:109], v[164:167], v[188:191], v[106:109]
	v_mfma_f32_16x16x32_bf16 v[98:101], v[172:175], v[188:191], v[98:101]
	v_mfma_f32_16x16x32_bf16 v[90:93], v[164:167], v[196:199], v[90:93]
	v_mfma_f32_16x16x32_bf16 v[82:85], v[172:175], v[196:199], v[82:85]
	v_mfma_f32_16x16x32_bf16 v[74:77], v[164:167], v[208:211], v[74:77]
	v_mfma_f32_16x16x32_bf16 v[66:69], v[172:175], v[208:211], v[66:69]
	v_mfma_f32_16x16x32_bf16 v[118:121], v[168:171], v[184:187], v[118:121]
	v_mfma_f32_16x16x32_bf16 v[114:117], v[176:179], v[184:187], v[114:117]
	v_mfma_f32_16x16x32_bf16 v[106:109], v[168:171], v[192:195], v[106:109]
	v_mfma_f32_16x16x32_bf16 v[98:101], v[176:179], v[192:195], v[98:101]
	v_mfma_f32_16x16x32_bf16 v[90:93], v[168:171], v[200:203], v[90:93]
	v_mfma_f32_16x16x32_bf16 v[82:85], v[176:179], v[200:203], v[82:85]
	v_mfma_f32_16x16x32_bf16 v[74:77], v[168:171], v[212:215], v[74:77]
	v_mfma_f32_16x16x32_bf16 v[66:69], v[176:179], v[212:215], v[66:69]
	s_setprio 0
	s_barrier
	s_add_i32 s38, s64, s33
	v_lshl_add_u64 v[204:205], v[204:205], 0, s[16:17]
	s_mov_b32 m0, s38
	ds_read_b128 v[180:183], v146 offset:49152
	ds_read_b128 v[184:187], v146 offset:50176
	ds_read_b128 v[188:191], v146 offset:51200
	ds_read_b128 v[192:195], v146 offset:52224
	ds_read_b128 v[196:199], v146 offset:53248
	ds_read_b128 v[200:203], v146 offset:54272
	ds_read_b128 v[208:211], v146 offset:55296
	ds_read_b128 v[212:215], v146 offset:56320
	global_load_lds_dwordx4 v[204:205], off
	s_add_i32 m0, s38, 0x2000
	s_add_u32 s2, s2, 0x100080
	v_lshl_add_u64 v[204:205], v[216:217], 0, s[16:17]
	s_addc_u32 s3, s3, 0
	s_add_i32 s38, s65, s33
	global_load_lds_dwordx4 v[204:205], off
	v_lshl_add_u64 v[204:205], s[2:3], 0, v[132:133]
	s_mov_b32 m0, s38
	s_nop 0
	global_load_lds_dwordx4 v[204:205], off
	v_lshl_add_u64 v[204:205], s[2:3], 0, v[136:137]
	s_add_i32 m0, s38, 0x2000
	s_nop 0
	global_load_lds_dwordx4 v[204:205], off
	v_lshl_add_u64 v[204:205], v[218:219], 0, s[16:17]
	s_mov_b32 m0, s44
	s_nop 0
	global_load_lds_dwordx4 v[204:205], off
	v_lshl_add_u64 v[204:205], v[220:221], 0, s[16:17]
	s_mov_b32 m0, s45
	s_nop 0
	global_load_lds_dwordx4 v[204:205], off
	s_waitcnt vmcnt(8)
	s_waitcnt lgkmcnt(0)
	s_barrier
	s_setprio 1
	s_waitcnt lgkmcnt(0)
	v_mfma_f32_16x16x32_bf16 v[62:65], v[148:151], v[180:183], v[62:65]
	v_mfma_f32_16x16x32_bf16 v[54:57], v[156:159], v[180:183], v[54:57]
	v_mfma_f32_16x16x32_bf16 v[46:49], v[148:151], v[188:191], v[46:49]
	v_mfma_f32_16x16x32_bf16 v[38:41], v[156:159], v[188:191], v[38:41]
	v_mfma_f32_16x16x32_bf16 v[30:33], v[148:151], v[196:199], v[30:33]
	v_mfma_f32_16x16x32_bf16 v[22:25], v[156:159], v[196:199], v[22:25]
	v_mfma_f32_16x16x32_bf16 v[14:17], v[148:151], v[208:211], v[14:17]
	v_mfma_f32_16x16x32_bf16 v[6:9], v[156:159], v[208:211], v[6:9]
	v_mfma_f32_16x16x32_bf16 v[62:65], v[152:155], v[184:187], v[62:65]
	v_mfma_f32_16x16x32_bf16 v[54:57], v[160:163], v[184:187], v[54:57]
	v_mfma_f32_16x16x32_bf16 v[46:49], v[152:155], v[192:195], v[46:49]
	v_mfma_f32_16x16x32_bf16 v[38:41], v[160:163], v[192:195], v[38:41]
	v_mfma_f32_16x16x32_bf16 v[30:33], v[152:155], v[200:203], v[30:33]
	v_mfma_f32_16x16x32_bf16 v[22:25], v[160:163], v[200:203], v[22:25]
	v_mfma_f32_16x16x32_bf16 v[14:17], v[152:155], v[212:215], v[14:17]
	v_mfma_f32_16x16x32_bf16 v[6:9], v[160:163], v[212:215], v[6:9]
	s_setprio 0
	s_setprio 1
	v_mfma_f32_16x16x32_bf16 v[58:61], v[164:167], v[180:183], v[58:61]
	v_mfma_f32_16x16x32_bf16 v[50:53], v[172:175], v[180:183], v[50:53]
	v_mfma_f32_16x16x32_bf16 v[42:45], v[164:167], v[188:191], v[42:45]
	v_mfma_f32_16x16x32_bf16 v[34:37], v[172:175], v[188:191], v[34:37]
	v_mfma_f32_16x16x32_bf16 v[26:29], v[164:167], v[196:199], v[26:29]
	v_mfma_f32_16x16x32_bf16 v[18:21], v[172:175], v[196:199], v[18:21]
	v_mfma_f32_16x16x32_bf16 v[10:13], v[164:167], v[208:211], v[10:13]
	v_mfma_f32_16x16x32_bf16 v[2:5], v[172:175], v[208:211], v[2:5]
	v_mfma_f32_16x16x32_bf16 v[58:61], v[168:171], v[184:187], v[58:61]
	v_mfma_f32_16x16x32_bf16 v[50:53], v[176:179], v[184:187], v[50:53]
	v_mfma_f32_16x16x32_bf16 v[42:45], v[168:171], v[192:195], v[42:45]
	v_mfma_f32_16x16x32_bf16 v[34:37], v[176:179], v[192:195], v[34:37]
	v_mfma_f32_16x16x32_bf16 v[26:29], v[168:171], v[200:203], v[26:29]
	v_mfma_f32_16x16x32_bf16 v[18:21], v[176:179], v[200:203], v[18:21]
	v_mfma_f32_16x16x32_bf16 v[10:13], v[168:171], v[212:215], v[10:13]
	v_mfma_f32_16x16x32_bf16 v[2:5], v[176:179], v[212:215], v[2:5]
	s_setprio 0
	s_barrier
	s_add_u32 s36, s36, 0x100
	s_addc_u32 s37, s37, 0
	s_add_u32 s59, s59, 0x100
	s_addc_u32 s60, s60, 0
	s_cmp_ge_i32 s61, s35
	s_mov_b32 s2, s61
	s_cbranch_scc1 .Lkpeel_exit_4

.Lkpeel_exit_4:
	v_readlane_b32 s59, v248, 41
	v_readlane_b32 s66, v248, 30
	v_readlane_b32 s67, v248, 31
	s_and_b64 vcc, exec, s[18:19]
	s_cbranch_vccz .LBB0_803

.LBB0_959:
	s_lshl_b32 s0, s16, 20
	s_and_b32 s0, s0, 0xff00000
	v_readlane_b32 s12, v248, 20
	v_readlane_b32 s13, v248, 21
	s_add_u32 s0, s12, s0
	s_addc_u32 s1, s13, 0
	s_lshr_b32 s12, s16, 13
	s_and_b32 s12, s12, 0x7ff80
	s_add_u32 s0, s0, s12
	s_addc_u32 s1, s1, 0
	s_lshl_b32 s13, s16, 12
	s_and_b32 s13, s13, 0xff00000
	v_readlane_b32 s24, v248, 51
	s_add_u32 s13, s24, s13
	v_readlane_b32 s24, v248, 53
	s_addc_u32 s24, s24, 0
	s_add_u32 s12, s13, s12
	s_addc_u32 s13, s24, 0
	s_cmp_lt_i32 s19, 1
	v_cmp_gt_i64_e64 s[16:17], s[16:17], -1
	s_cbranch_scc1 .LBB0_976
	s_and_b64 s[36:37], s[16:17], exec
	s_cselect_b32 s24, s1, s35
	s_cselect_b32 s53, s0, s34
	s_cselect_b32 s56, s13, s3
	s_cselect_b32 s57, s12, s2
	s_add_i32 s58, s19, -2
	s_add_u32 s34, s34, 0x80080
	s_addc_u32 s35, s35, 0
	s_add_u32 s59, s2, 0x100
	s_addc_u32 s60, s3, 0
	s_mov_b32 s2, 0
	s_add_i32 s61, s2, 2
	s_add_u32 s3, s34, 0xfff80080
	s_addc_u32 s36, s35, -1
	s_add_i32 s64, 0, 0x10000
	s_cmp_eq_u32 s58, s2
	s_cselect_b32 s37, s24, s36
	s_cselect_b32 s36, s53, s3
	v_add_u32_e32 v142, s64, v131
	s_cselect_b32 s3, s56, s60
	s_cselect_b32 s2, s57, s59
	s_add_i32 s66, 0, 0x14000
	ds_read_b128 v[148:151], v142
	ds_read_b128 v[152:155], v142 offset:1024
	ds_read_b128 v[156:159], v142 offset:2048
	ds_read_b128 v[160:163], v142 offset:3072
	v_add_u32_e32 v142, s66, v131
	ds_read_b128 v[188:191], v142
	ds_read_b128 v[192:195], v142 offset:1024
	ds_read_b128 v[196:199], v142 offset:2048
	ds_read_b128 v[200:203], v142 offset:3072
	v_lshl_add_u64 v[236:237], s[34:35], 0, v[144:145]
	s_add_i32 m0, s40, 0xc000
	ds_read_b128 v[204:207], v186
	ds_read_b128 v[208:211], v186 offset:1024
	ds_read_b128 v[212:215], v186 offset:2048
	ds_read_b128 v[216:219], v186 offset:3072
	ds_read_b128 v[220:223], v186 offset:4096
	ds_read_b128 v[224:227], v186 offset:5120
	ds_read_b128 v[228:231], v186 offset:6144
	ds_read_b128 v[232:235], v186 offset:7168
	global_load_lds_dwordx4 v[236:237], off
	v_lshl_add_u64 v[236:237], s[34:35], 0, v[146:147]
	s_add_i32 m0, s40, 0xe000
	s_nop 0
	global_load_lds_dwordx4 v[236:237], off
	s_waitcnt vmcnt(8)
	s_waitcnt lgkmcnt(0)
	s_barrier
	s_setprio 1
	s_waitcnt lgkmcnt(0)
	v_mfma_i32_16x16x64_i8 v[126:129], v[148:151], v[204:207], 0
	v_mfma_i32_16x16x64_i8 v[122:125], v[156:159], v[204:207], 0
	v_mfma_i32_16x16x64_i8 v[118:121], v[148:151], v[212:215], 0
	v_mfma_i32_16x16x64_i8 v[114:117], v[156:159], v[212:215], 0
	v_mfma_i32_16x16x64_i8 v[110:113], v[148:151], v[220:223], 0
	v_mfma_i32_16x16x64_i8 v[106:109], v[156:159], v[220:223], 0
	v_mfma_i32_16x16x64_i8 v[102:105], v[148:151], v[228:231], 0
	v_mfma_i32_16x16x64_i8 v[98:101], v[156:159], v[228:231], 0
	v_mfma_i32_16x16x64_i8 v[126:129], v[152:155], v[208:211], v[126:129]
	v_mfma_i32_16x16x64_i8 v[122:125], v[160:163], v[208:211], v[122:125]
	v_mfma_i32_16x16x64_i8 v[118:121], v[152:155], v[216:219], v[118:121]
	v_mfma_i32_16x16x64_i8 v[114:117], v[160:163], v[216:219], v[114:117]
	v_mfma_i32_16x16x64_i8 v[110:113], v[152:155], v[224:227], v[110:113]
	v_mfma_i32_16x16x64_i8 v[106:109], v[160:163], v[224:227], v[106:109]
	v_mfma_i32_16x16x64_i8 v[102:105], v[152:155], v[232:235], v[102:105]
	v_mfma_i32_16x16x64_i8 v[98:101], v[160:163], v[232:235], v[98:101]
	s_setprio 0
	s_setprio 1
	v_mfma_i32_16x16x64_i8 v[94:97], v[188:191], v[204:207], 0
	v_mfma_i32_16x16x64_i8 v[90:93], v[196:199], v[204:207], 0
	v_mfma_i32_16x16x64_i8 v[86:89], v[188:191], v[212:215], 0
	v_mfma_i32_16x16x64_i8 v[82:85], v[196:199], v[212:215], 0
	v_mfma_i32_16x16x64_i8 v[78:81], v[188:191], v[220:223], 0
	v_mfma_i32_16x16x64_i8 v[74:77], v[196:199], v[220:223], 0
	v_mfma_i32_16x16x64_i8 v[70:73], v[188:191], v[228:231], 0
	v_mfma_i32_16x16x64_i8 v[66:69], v[196:199], v[228:231], 0
	v_mfma_i32_16x16x64_i8 v[94:97], v[192:195], v[208:211], v[94:97]
	v_mfma_i32_16x16x64_i8 v[90:93], v[200:203], v[208:211], v[90:93]
	v_mfma_i32_16x16x64_i8 v[86:89], v[192:195], v[216:219], v[86:89]
	v_mfma_i32_16x16x64_i8 v[82:85], v[200:203], v[216:219], v[82:85]
	v_mfma_i32_16x16x64_i8 v[78:81], v[192:195], v[224:227], v[78:81]
	v_mfma_i32_16x16x64_i8 v[74:77], v[200:203], v[224:227], v[74:77]
	v_mfma_i32_16x16x64_i8 v[70:73], v[192:195], v[232:235], v[70:73]
	v_mfma_i32_16x16x64_i8 v[66:69], v[200:203], v[232:235], v[66:69]
	s_setprio 0
	s_barrier
	s_add_i32 s64, s64, s39
	v_lshl_add_u64 v[236:237], s[2:3], 0, v[136:137]
	s_mov_b32 m0, s64
	ds_read_b128 v[204:207], v186 offset:16384
	ds_read_b128 v[208:211], v186 offset:17408
	ds_read_b128 v[212:215], v186 offset:18432
	ds_read_b128 v[216:219], v186 offset:19456
	ds_read_b128 v[220:223], v186 offset:20480
	ds_read_b128 v[224:227], v186 offset:21504
	ds_read_b128 v[228:231], v186 offset:22528
	ds_read_b128 v[232:235], v186 offset:23552
	global_load_lds_dwordx4 v[236:237], off
	s_add_i32 m0, s64, 0x2000
	s_add_u32 s64, s2, 0x80000
	v_lshl_add_u64 v[238:239], s[2:3], 0, v[140:141]
	s_addc_u32 s65, s3, 0
	s_add_i32 s66, s66, s39
	global_load_lds_dwordx4 v[238:239], off
	v_lshl_add_u64 v[240:241], s[64:65], 0, v[136:137]
	s_mov_b32 m0, s66
	v_lshl_add_u64 v[242:243], s[36:37], 0, v[138:139]
	global_load_lds_dwordx4 v[240:241], off
	v_lshl_add_u64 v[240:241], s[64:65], 0, v[140:141]
	s_add_i32 m0, s66, 0x2000
	s_nop 0
	global_load_lds_dwordx4 v[240:241], off
	v_lshl_add_u64 v[240:241], s[36:37], 0, v[134:135]
	s_mov_b32 m0, s40
	s_nop 0
	global_load_lds_dwordx4 v[240:241], off
	s_mov_b32 m0, s41
	s_nop 0
	global_load_lds_dwordx4 v[242:243], off
	s_waitcnt vmcnt(8)
	s_waitcnt lgkmcnt(0)
	s_barrier
	s_setprio 1
	s_waitcnt lgkmcnt(0)
	v_mfma_i32_16x16x64_i8 v[62:65], v[148:151], v[204:207], 0
	v_mfma_i32_16x16x64_i8 v[58:61], v[156:159], v[204:207], 0
	v_mfma_i32_16x16x64_i8 v[54:57], v[148:151], v[212:215], 0
	v_mfma_i32_16x16x64_i8 v[50:53], v[156:159], v[212:215], 0
	v_mfma_i32_16x16x64_i8 v[46:49], v[148:151], v[220:223], 0
	v_mfma_i32_16x16x64_i8 v[42:45], v[156:159], v[220:223], 0
	v_mfma_i32_16x16x64_i8 v[38:41], v[148:151], v[228:231], 0
	v_mfma_i32_16x16x64_i8 v[34:37], v[156:159], v[228:231], 0
	v_mfma_i32_16x16x64_i8 v[62:65], v[152:155], v[208:211], v[62:65]
	v_mfma_i32_16x16x64_i8 v[58:61], v[160:163], v[208:211], v[58:61]
	v_mfma_i32_16x16x64_i8 v[54:57], v[152:155], v[216:219], v[54:57]
	v_mfma_i32_16x16x64_i8 v[50:53], v[160:163], v[216:219], v[50:53]
	v_mfma_i32_16x16x64_i8 v[46:49], v[152:155], v[224:227], v[46:49]
	v_mfma_i32_16x16x64_i8 v[42:45], v[160:163], v[224:227], v[42:45]
	v_mfma_i32_16x16x64_i8 v[38:41], v[152:155], v[232:235], v[38:41]
	v_mfma_i32_16x16x64_i8 v[34:37], v[160:163], v[232:235], v[34:37]
	s_setprio 0
	s_setprio 1
	v_mfma_i32_16x16x64_i8 v[30:33], v[188:191], v[204:207], 0
	v_mfma_i32_16x16x64_i8 v[26:29], v[196:199], v[204:207], 0
	v_mfma_i32_16x16x64_i8 v[22:25], v[188:191], v[212:215], 0
	v_mfma_i32_16x16x64_i8 v[18:21], v[196:199], v[212:215], 0
	v_mfma_i32_16x16x64_i8 v[14:17], v[188:191], v[220:223], 0
	v_mfma_i32_16x16x64_i8 v[10:13], v[196:199], v[220:223], 0
	v_mfma_i32_16x16x64_i8 v[6:9], v[188:191], v[228:231], 0
	v_mfma_i32_16x16x64_i8 v[2:5], v[196:199], v[228:231], 0
	v_mfma_i32_16x16x64_i8 v[30:33], v[192:195], v[208:211], v[30:33]
	v_mfma_i32_16x16x64_i8 v[26:29], v[200:203], v[208:211], v[26:29]
	v_mfma_i32_16x16x64_i8 v[22:25], v[192:195], v[216:219], v[22:25]
	v_mfma_i32_16x16x64_i8 v[18:21], v[200:203], v[216:219], v[18:21]
	v_mfma_i32_16x16x64_i8 v[14:17], v[192:195], v[224:227], v[14:17]
	v_mfma_i32_16x16x64_i8 v[10:13], v[200:203], v[224:227], v[10:13]
	v_mfma_i32_16x16x64_i8 v[6:9], v[192:195], v[232:235], v[6:9]
	v_mfma_i32_16x16x64_i8 v[2:5], v[200:203], v[232:235], v[2:5]
	s_setprio 0
	s_barrier
	s_add_i32 s64, 0, 0x18000
	v_add_u32_e32 v142, s64, v131
	s_add_i32 s65, 0, 0x1c000
	ds_read_b128 v[148:151], v142
	ds_read_b128 v[152:155], v142 offset:1024
	ds_read_b128 v[156:159], v142 offset:2048
	ds_read_b128 v[160:163], v142 offset:3072
	v_add_u32_e32 v142, s65, v131
	ds_read_b128 v[188:191], v142
	ds_read_b128 v[192:195], v142 offset:1024
	ds_read_b128 v[196:199], v142 offset:2048
	ds_read_b128 v[200:203], v142 offset:3072
	s_add_u32 s36, s36, 0x80000
	s_addc_u32 s37, s37, 0
	s_mov_b32 m0, s42
	v_lshl_add_u64 v[244:245], s[36:37], 0, v[134:135]
	ds_read_b128 v[204:207], v186 offset:32768
	ds_read_b128 v[208:211], v186 offset:33792
	ds_read_b128 v[212:215], v186 offset:34816
	ds_read_b128 v[216:219], v186 offset:35840
	ds_read_b128 v[220:223], v186 offset:36864
	ds_read_b128 v[224:227], v186 offset:37888
	ds_read_b128 v[228:231], v186 offset:38912
	ds_read_b128 v[232:235], v186 offset:39936
	global_load_lds_dwordx4 v[244:245], off
	v_lshl_add_u64 v[244:245], s[36:37], 0, v[138:139]
	s_mov_b32 m0, s43
	s_nop 0
	global_load_lds_dwordx4 v[244:245], off
	s_waitcnt vmcnt(8)
	s_waitcnt lgkmcnt(0)
	s_barrier
	s_setprio 1
	s_waitcnt lgkmcnt(0)
	v_mfma_i32_16x16x64_i8 v[126:129], v[148:151], v[204:207], v[126:129]
	v_mfma_i32_16x16x64_i8 v[122:125], v[156:159], v[204:207], v[122:125]
	v_mfma_i32_16x16x64_i8 v[118:121], v[148:151], v[212:215], v[118:121]
	v_mfma_i32_16x16x64_i8 v[114:117], v[156:159], v[212:215], v[114:117]
	v_mfma_i32_16x16x64_i8 v[110:113], v[148:151], v[220:223], v[110:113]
	v_mfma_i32_16x16x64_i8 v[106:109], v[156:159], v[220:223], v[106:109]
	v_mfma_i32_16x16x64_i8 v[102:105], v[148:151], v[228:231], v[102:105]
	v_mfma_i32_16x16x64_i8 v[98:101], v[156:159], v[228:231], v[98:101]
	v_mfma_i32_16x16x64_i8 v[126:129], v[152:155], v[208:211], v[126:129]
	v_mfma_i32_16x16x64_i8 v[122:125], v[160:163], v[208:211], v[122:125]
	v_mfma_i32_16x16x64_i8 v[118:121], v[152:155], v[216:219], v[118:121]
	v_mfma_i32_16x16x64_i8 v[114:117], v[160:163], v[216:219], v[114:117]
	v_mfma_i32_16x16x64_i8 v[110:113], v[152:155], v[224:227], v[110:113]
	v_mfma_i32_16x16x64_i8 v[106:109], v[160:163], v[224:227], v[106:109]
	v_mfma_i32_16x16x64_i8 v[102:105], v[152:155], v[232:235], v[102:105]
	v_mfma_i32_16x16x64_i8 v[98:101], v[160:163], v[232:235], v[98:101]
	s_setprio 0
	s_setprio 1
	v_mfma_i32_16x16x64_i8 v[94:97], v[188:191], v[204:207], v[94:97]
	v_mfma_i32_16x16x64_i8 v[90:93], v[196:199], v[204:207], v[90:93]
	v_mfma_i32_16x16x64_i8 v[86:89], v[188:191], v[212:215], v[86:89]
	v_mfma_i32_16x16x64_i8 v[82:85], v[196:199], v[212:215], v[82:85]
	v_mfma_i32_16x16x64_i8 v[78:81], v[188:191], v[220:223], v[78:81]
	v_mfma_i32_16x16x64_i8 v[74:77], v[196:199], v[220:223], v[74:77]
	v_mfma_i32_16x16x64_i8 v[70:73], v[188:191], v[228:231], v[70:73]
	v_mfma_i32_16x16x64_i8 v[66:69], v[196:199], v[228:231], v[66:69]
	v_mfma_i32_16x16x64_i8 v[94:97], v[192:195], v[208:211], v[94:97]
	v_mfma_i32_16x16x64_i8 v[90:93], v[200:203], v[208:211], v[90:93]
	v_mfma_i32_16x16x64_i8 v[86:89], v[192:195], v[216:219], v[86:89]
	v_mfma_i32_16x16x64_i8 v[82:85], v[200:203], v[216:219], v[82:85]
	v_mfma_i32_16x16x64_i8 v[78:81], v[192:195], v[224:227], v[78:81]
	v_mfma_i32_16x16x64_i8 v[74:77], v[200:203], v[224:227], v[74:77]
	v_mfma_i32_16x16x64_i8 v[70:73], v[192:195], v[232:235], v[70:73]
	v_mfma_i32_16x16x64_i8 v[66:69], v[200:203], v[232:235], v[66:69]
	s_setprio 0
	s_barrier
	s_add_i32 s36, s64, s39
	v_lshl_add_u64 v[236:237], v[236:237], 0, s[28:29]
	s_mov_b32 m0, s36
	ds_read_b128 v[204:207], v186 offset:49152
	ds_read_b128 v[208:211], v186 offset:50176
	ds_read_b128 v[212:215], v186 offset:51200
	ds_read_b128 v[216:219], v186 offset:52224
	ds_read_b128 v[220:223], v186 offset:53248
	ds_read_b128 v[224:227], v186 offset:54272
	ds_read_b128 v[228:231], v186 offset:55296
	ds_read_b128 v[232:235], v186 offset:56320
	global_load_lds_dwordx4 v[236:237], off
	s_add_i32 m0, s36, 0x2000
	s_add_u32 s2, s2, 0x80080
	v_lshl_add_u64 v[236:237], v[238:239], 0, s[28:29]
	s_addc_u32 s3, s3, 0
	s_add_i32 s36, s65, s39
	global_load_lds_dwordx4 v[236:237], off
	v_lshl_add_u64 v[236:237], s[2:3], 0, v[136:137]
	s_mov_b32 m0, s36
	s_nop 0
	global_load_lds_dwordx4 v[236:237], off
	v_lshl_add_u64 v[236:237], s[2:3], 0, v[140:141]
	s_add_i32 m0, s36, 0x2000
	s_nop 0
	global_load_lds_dwordx4 v[236:237], off
	v_lshl_add_u64 v[236:237], v[240:241], 0, s[28:29]
	s_mov_b32 m0, s45
	s_nop 0
	global_load_lds_dwordx4 v[236:237], off
	v_lshl_add_u64 v[236:237], v[242:243], 0, s[28:29]
	s_mov_b32 m0, s52
	s_nop 0
	global_load_lds_dwordx4 v[236:237], off
	s_waitcnt vmcnt(8)
	s_waitcnt lgkmcnt(0)
	s_barrier
	s_setprio 1
	s_waitcnt lgkmcnt(0)
	v_mfma_i32_16x16x64_i8 v[62:65], v[148:151], v[204:207], v[62:65]
	v_mfma_i32_16x16x64_i8 v[58:61], v[156:159], v[204:207], v[58:61]
	v_mfma_i32_16x16x64_i8 v[54:57], v[148:151], v[212:215], v[54:57]
	v_mfma_i32_16x16x64_i8 v[50:53], v[156:159], v[212:215], v[50:53]
	v_mfma_i32_16x16x64_i8 v[46:49], v[148:151], v[220:223], v[46:49]
	v_mfma_i32_16x16x64_i8 v[42:45], v[156:159], v[220:223], v[42:45]
	v_mfma_i32_16x16x64_i8 v[38:41], v[148:151], v[228:231], v[38:41]
	v_mfma_i32_16x16x64_i8 v[34:37], v[156:159], v[228:231], v[34:37]
	v_mfma_i32_16x16x64_i8 v[62:65], v[152:155], v[208:211], v[62:65]
	v_mfma_i32_16x16x64_i8 v[58:61], v[160:163], v[208:211], v[58:61]
	v_mfma_i32_16x16x64_i8 v[54:57], v[152:155], v[216:219], v[54:57]
	v_mfma_i32_16x16x64_i8 v[50:53], v[160:163], v[216:219], v[50:53]
	v_mfma_i32_16x16x64_i8 v[46:49], v[152:155], v[224:227], v[46:49]
	v_mfma_i32_16x16x64_i8 v[42:45], v[160:163], v[224:227], v[42:45]
	v_mfma_i32_16x16x64_i8 v[38:41], v[152:155], v[232:235], v[38:41]
	v_mfma_i32_16x16x64_i8 v[34:37], v[160:163], v[232:235], v[34:37]
	s_setprio 0
	s_setprio 1
	v_mfma_i32_16x16x64_i8 v[30:33], v[188:191], v[204:207], v[30:33]
	v_mfma_i32_16x16x64_i8 v[26:29], v[196:199], v[204:207], v[26:29]
	v_mfma_i32_16x16x64_i8 v[22:25], v[188:191], v[212:215], v[22:25]
	v_mfma_i32_16x16x64_i8 v[18:21], v[196:199], v[212:215], v[18:21]
	v_mfma_i32_16x16x64_i8 v[14:17], v[188:191], v[220:223], v[14:17]
	v_mfma_i32_16x16x64_i8 v[10:13], v[196:199], v[220:223], v[10:13]
	v_mfma_i32_16x16x64_i8 v[6:9], v[188:191], v[228:231], v[6:9]
	v_mfma_i32_16x16x64_i8 v[2:5], v[196:199], v[228:231], v[2:5]
	v_mfma_i32_16x16x64_i8 v[30:33], v[192:195], v[208:211], v[30:33]
	v_mfma_i32_16x16x64_i8 v[26:29], v[200:203], v[208:211], v[26:29]
	v_mfma_i32_16x16x64_i8 v[22:25], v[192:195], v[216:219], v[22:25]
	v_mfma_i32_16x16x64_i8 v[18:21], v[200:203], v[216:219], v[18:21]
	v_mfma_i32_16x16x64_i8 v[14:17], v[192:195], v[224:227], v[14:17]
	v_mfma_i32_16x16x64_i8 v[10:13], v[200:203], v[224:227], v[10:13]
	v_mfma_i32_16x16x64_i8 v[6:9], v[192:195], v[232:235], v[6:9]
	v_mfma_i32_16x16x64_i8 v[2:5], v[200:203], v[232:235], v[2:5]
	s_setprio 0
	s_barrier
	s_add_u32 s34, s34, 0x100
	s_addc_u32 s35, s35, 0
	s_add_u32 s59, s59, 0x100
	s_addc_u32 s60, s60, 0
	s_cmp_ge_i32 s61, s19
	s_mov_b32 s2, s61
	s_cbranch_scc1 .Lkpeel_exit_5

.Lkpeel_exit_5:
	v_cvt_f32_i32_e32 v156, v126
	v_cvt_f32_i32_e32 v157, v127
	v_cvt_f32_i32_e32 v158, v128
	v_cvt_f32_i32_e32 v159, v129
	v_cvt_f32_i32_e32 v148, v122
	v_cvt_f32_i32_e32 v149, v123
	v_cvt_f32_i32_e32 v150, v124
	v_cvt_f32_i32_e32 v151, v125
	v_cvt_f32_i32_e32 v122, v118
	v_cvt_f32_i32_e32 v123, v119
	v_cvt_f32_i32_e32 v124, v120
	v_cvt_f32_i32_e32 v125, v121
	v_cvt_f32_i32_e32 v114, v114
	v_cvt_f32_i32_e32 v115, v115
	v_cvt_f32_i32_e32 v116, v116
	v_cvt_f32_i32_e32 v117, v117
	v_cvt_f32_i32_e32 v110, v110
	v_cvt_f32_i32_e32 v111, v111
	v_cvt_f32_i32_e32 v112, v112
	v_cvt_f32_i32_e32 v113, v113
	v_cvt_f32_i32_e32 v106, v106
	v_cvt_f32_i32_e32 v107, v107
	v_cvt_f32_i32_e32 v108, v108
	v_cvt_f32_i32_e32 v109, v109
	v_cvt_f32_i32_e32 v102, v102
	v_cvt_f32_i32_e32 v103, v103
	v_cvt_f32_i32_e32 v104, v104
	v_cvt_f32_i32_e32 v105, v105
	v_cvt_f32_i32_e32 v98, v98
	v_cvt_f32_i32_e32 v99, v99
	v_cvt_f32_i32_e32 v100, v100
	v_cvt_f32_i32_e32 v101, v101
	v_cvt_f32_i32_e32 v162, v94
	v_cvt_f32_i32_e32 v163, v95
	v_cvt_f32_i32_e32 v160, v96
	v_cvt_f32_i32_e32 v161, v97
	v_cvt_f32_i32_e32 v154, v90
	v_cvt_f32_i32_e32 v155, v91
	v_cvt_f32_i32_e32 v152, v92
	v_cvt_f32_i32_e32 v153, v93
	v_cvt_f32_i32_e32 v128, v86
	v_cvt_f32_i32_e32 v129, v87
	v_cvt_f32_i32_e32 v126, v88
	v_cvt_f32_i32_e32 v127, v89
	v_cvt_f32_i32_e32 v120, v82
	v_cvt_f32_i32_e32 v121, v83
	v_cvt_f32_i32_e32 v118, v84
	v_cvt_f32_i32_e32 v119, v85
	v_cvt_f32_i32_e32 v96, v78
	v_cvt_f32_i32_e32 v97, v79
	v_cvt_f32_i32_e32 v94, v80
	v_cvt_f32_i32_e32 v95, v81
	v_cvt_f32_i32_e32 v92, v74
	v_cvt_f32_i32_e32 v93, v75
	v_cvt_f32_i32_e32 v90, v76
	v_cvt_f32_i32_e32 v91, v77
	v_cvt_f32_i32_e32 v88, v70
	v_cvt_f32_i32_e32 v89, v71
	v_cvt_f32_i32_e32 v86, v72
	v_cvt_f32_i32_e32 v87, v73
	v_cvt_f32_i32_e32 v84, v66
	v_cvt_f32_i32_e32 v85, v67
	v_cvt_f32_i32_e32 v82, v68
	v_cvt_f32_i32_e32 v83, v69
	v_cvt_f32_i32_e32 v74, v62
	v_cvt_f32_i32_e32 v75, v63
	v_cvt_f32_i32_e32 v76, v64
	v_cvt_f32_i32_e32 v77, v65
	v_cvt_f32_i32_e32 v66, v58
	v_cvt_f32_i32_e32 v67, v59
	v_cvt_f32_i32_e32 v68, v60
	v_cvt_f32_i32_e32 v69, v61
	v_cvt_f32_i32_e32 v58, v54
	v_cvt_f32_i32_e32 v59, v55
	v_cvt_f32_i32_e32 v60, v56
	v_cvt_f32_i32_e32 v61, v57
	v_cvt_f32_i32_e32 v50, v50
	v_cvt_f32_i32_e32 v51, v51
	v_cvt_f32_i32_e32 v52, v52
	v_cvt_f32_i32_e32 v53, v53
	v_cvt_f32_i32_e32 v46, v46
	v_cvt_f32_i32_e32 v47, v47
	v_cvt_f32_i32_e32 v48, v48
	v_cvt_f32_i32_e32 v49, v49
	v_cvt_f32_i32_e32 v42, v42
	v_cvt_f32_i32_e32 v43, v43
	v_cvt_f32_i32_e32 v44, v44
	v_cvt_f32_i32_e32 v45, v45
	v_cvt_f32_i32_e32 v38, v38
	v_cvt_f32_i32_e32 v39, v39
	v_cvt_f32_i32_e32 v40, v40
	v_cvt_f32_i32_e32 v41, v41
	v_cvt_f32_i32_e32 v34, v34
	v_cvt_f32_i32_e32 v35, v35
	v_cvt_f32_i32_e32 v36, v36
	v_cvt_f32_i32_e32 v37, v37
	v_cvt_f32_i32_e32 v80, v30
	v_cvt_f32_i32_e32 v81, v31
	v_cvt_f32_i32_e32 v78, v32
	v_cvt_f32_i32_e32 v79, v33
	v_cvt_f32_i32_e32 v72, v26
	v_cvt_f32_i32_e32 v73, v27
	v_cvt_f32_i32_e32 v70, v28
	v_cvt_f32_i32_e32 v71, v29
	v_cvt_f32_i32_e32 v64, v22
	v_cvt_f32_i32_e32 v65, v23
	v_cvt_f32_i32_e32 v62, v24
	v_cvt_f32_i32_e32 v63, v25
	v_cvt_f32_i32_e32 v56, v18
	v_cvt_f32_i32_e32 v57, v19
	v_cvt_f32_i32_e32 v54, v20
	v_cvt_f32_i32_e32 v55, v21
	v_cvt_f32_i32_e32 v32, v14
	v_cvt_f32_i32_e32 v33, v15
	v_cvt_f32_i32_e32 v30, v16
	v_cvt_f32_i32_e32 v31, v17
	v_cvt_f32_i32_e32 v28, v10
	v_cvt_f32_i32_e32 v29, v11
	v_cvt_f32_i32_e32 v26, v12
	v_cvt_f32_i32_e32 v27, v13
	v_cvt_f32_i32_e32 v24, v6
	v_cvt_f32_i32_e32 v25, v7
	v_cvt_f32_i32_e32 v22, v8
	v_cvt_f32_i32_e32 v23, v9
	v_cvt_f32_i32_e32 v20, v2
	v_cvt_f32_i32_e32 v21, v3
	v_cvt_f32_i32_e32 v18, v4
	v_cvt_f32_i32_e32 v19, v5
	v_readlane_b32 s59, v248, 41
	v_readlane_b32 s66, v248, 30
	v_readlane_b32 s67, v248, 31
	s_and_b64 vcc, exec, s[50:51]
	s_cbranch_vccz .LBB0_964

.LBB0_1126:
	s_cmp_lt_i32 s29, 1
	s_cbranch_scc1 .LBB0_1148
	s_add_i32 s18, s29, -2
	s_add_u32 s30, s30, 0x2b0080
	s_addc_u32 s31, s31, 0
	s_add_u32 s28, s2, 0x100
	s_addc_u32 s52, s3, 0
	s_mov_b32 s2, 0
	ds_read_b128 v[148:151], v145
	ds_read_b128 v[152:155], v145 offset:1024
	ds_read_b128 v[156:159], v145 offset:2048
	ds_read_b128 v[160:163], v145 offset:3072
	ds_read_b128 v[164:167], v146
	ds_read_b128 v[170:173], v146 offset:1024
	ds_read_b128 v[174:177], v146 offset:2048
	ds_read_b128 v[178:181], v146 offset:3072
	s_add_i32 s53, s2, 2
	s_add_u32 s3, s30, 0xffd50080
	s_addc_u32 s34, s31, -1
	s_cmp_eq_u32 s18, s2
	s_cselect_b32 s2, s26, s28
	s_cselect_b32 s35, s25, s34
	s_cselect_b32 s34, s24, s3
	s_cselect_b32 s3, s27, s52
	v_lshl_add_u64 v[214:215], s[30:31], 0, v[140:141]
	s_add_i32 m0, s37, 0xc000
	ds_read_b128 v[182:185], v147
	ds_read_b128 v[186:189], v147 offset:1024
	ds_read_b128 v[190:193], v147 offset:2048
	ds_read_b128 v[194:197], v147 offset:3072
	ds_read_b128 v[198:201], v147 offset:4096
	ds_read_b128 v[202:205], v147 offset:5120
	ds_read_b128 v[206:209], v147 offset:6144
	ds_read_b128 v[210:213], v147 offset:7168
	global_load_lds_dwordx4 v[214:215], off
	v_lshl_add_u64 v[214:215], s[30:31], 0, v[142:143]
	s_add_i32 m0, s37, 0xe000
	s_nop 0
	global_load_lds_dwordx4 v[214:215], off
	s_waitcnt vmcnt(8)
	s_waitcnt lgkmcnt(0)
	s_barrier
	s_setprio 1
	s_waitcnt lgkmcnt(0)
	v_mfma_f32_16x16x32_bf16 v[124:127], v[148:151], v[182:185], 0
	v_mfma_f32_16x16x32_bf16 v[120:123], v[156:159], v[182:185], 0
	v_mfma_f32_16x16x32_bf16 v[108:111], v[148:151], v[190:193], 0
	v_mfma_f32_16x16x32_bf16 v[100:103], v[156:159], v[190:193], 0
	v_mfma_f32_16x16x32_bf16 v[92:95], v[148:151], v[198:201], 0
	v_mfma_f32_16x16x32_bf16 v[84:87], v[156:159], v[198:201], 0
	v_mfma_f32_16x16x32_bf16 v[76:79], v[148:151], v[206:209], 0
	v_mfma_f32_16x16x32_bf16 v[68:71], v[156:159], v[206:209], 0
	v_mfma_f32_16x16x32_bf16 v[124:127], v[152:155], v[186:189], v[124:127]
	v_mfma_f32_16x16x32_bf16 v[120:123], v[160:163], v[186:189], v[120:123]
	v_mfma_f32_16x16x32_bf16 v[108:111], v[152:155], v[194:197], v[108:111]
	v_mfma_f32_16x16x32_bf16 v[100:103], v[160:163], v[194:197], v[100:103]
	v_mfma_f32_16x16x32_bf16 v[92:95], v[152:155], v[202:205], v[92:95]
	v_mfma_f32_16x16x32_bf16 v[84:87], v[160:163], v[202:205], v[84:87]
	v_mfma_f32_16x16x32_bf16 v[76:79], v[152:155], v[210:213], v[76:79]
	v_mfma_f32_16x16x32_bf16 v[68:71], v[160:163], v[210:213], v[68:71]
	s_setprio 0
	s_setprio 1
	v_mfma_f32_16x16x32_bf16 v[116:119], v[164:167], v[182:185], 0
	v_mfma_f32_16x16x32_bf16 v[112:115], v[174:177], v[182:185], 0
	v_mfma_f32_16x16x32_bf16 v[104:107], v[164:167], v[190:193], 0
	v_mfma_f32_16x16x32_bf16 v[96:99], v[174:177], v[190:193], 0
	v_mfma_f32_16x16x32_bf16 v[88:91], v[164:167], v[198:201], 0
	v_mfma_f32_16x16x32_bf16 v[80:83], v[174:177], v[198:201], 0
	v_mfma_f32_16x16x32_bf16 v[72:75], v[164:167], v[206:209], 0
	v_mfma_f32_16x16x32_bf16 v[64:67], v[174:177], v[206:209], 0
	v_mfma_f32_16x16x32_bf16 v[116:119], v[170:173], v[186:189], v[116:119]
	v_mfma_f32_16x16x32_bf16 v[112:115], v[178:181], v[186:189], v[112:115]
	v_mfma_f32_16x16x32_bf16 v[104:107], v[170:173], v[194:197], v[104:107]
	v_mfma_f32_16x16x32_bf16 v[96:99], v[178:181], v[194:197], v[96:99]
	v_mfma_f32_16x16x32_bf16 v[88:91], v[170:173], v[202:205], v[88:91]
	v_mfma_f32_16x16x32_bf16 v[80:83], v[178:181], v[202:205], v[80:83]
	v_mfma_f32_16x16x32_bf16 v[72:75], v[170:173], v[210:213], v[72:75]
	v_mfma_f32_16x16x32_bf16 v[64:67], v[178:181], v[210:213], v[64:67]
	s_setprio 0
	s_barrier
	s_add_i32 s56, s46, s33
	v_lshl_add_u64 v[214:215], s[2:3], 0, v[134:135]
	s_mov_b32 m0, s56
	ds_read_b128 v[182:185], v147 offset:16384
	ds_read_b128 v[186:189], v147 offset:17408
	ds_read_b128 v[190:193], v147 offset:18432
	ds_read_b128 v[194:197], v147 offset:19456
	ds_read_b128 v[198:201], v147 offset:20480
	ds_read_b128 v[202:205], v147 offset:21504
	ds_read_b128 v[206:209], v147 offset:22528
	ds_read_b128 v[210:213], v147 offset:23552
	global_load_lds_dwordx4 v[214:215], off
	s_add_i32 m0, s56, 0x2000
	s_add_u32 s56, s2, 0x2b0000
	v_lshl_add_u64 v[216:217], s[2:3], 0, v[138:139]
	s_addc_u32 s57, s3, 0
	s_add_i32 s58, s47, s33
	global_load_lds_dwordx4 v[216:217], off
	v_lshl_add_u64 v[218:219], s[56:57], 0, v[134:135]
	s_mov_b32 m0, s58
	v_lshl_add_u64 v[220:221], s[34:35], 0, v[136:137]
	global_load_lds_dwordx4 v[218:219], off
	v_lshl_add_u64 v[218:219], s[56:57], 0, v[138:139]
	s_add_i32 m0, s58, 0x2000
	s_nop 0
	global_load_lds_dwordx4 v[218:219], off
	v_lshl_add_u64 v[218:219], s[34:35], 0, v[128:129]
	s_mov_b32 m0, s37
	s_nop 0
	global_load_lds_dwordx4 v[218:219], off
	s_mov_b32 m0, s38
	s_nop 0
	global_load_lds_dwordx4 v[220:221], off
	s_waitcnt vmcnt(8)
	s_waitcnt lgkmcnt(0)
	s_barrier
	s_setprio 1
	s_waitcnt lgkmcnt(0)
	v_mfma_f32_16x16x32_bf16 v[60:63], v[148:151], v[182:185], 0
	v_mfma_f32_16x16x32_bf16 v[52:55], v[156:159], v[182:185], 0
	v_mfma_f32_16x16x32_bf16 v[44:47], v[148:151], v[190:193], 0
	v_mfma_f32_16x16x32_bf16 v[36:39], v[156:159], v[190:193], 0
	v_mfma_f32_16x16x32_bf16 v[28:31], v[148:151], v[198:201], 0
	v_mfma_f32_16x16x32_bf16 v[20:23], v[156:159], v[198:201], 0
	v_mfma_f32_16x16x32_bf16 v[12:15], v[148:151], v[206:209], 0
	v_mfma_f32_16x16x32_bf16 v[4:7], v[156:159], v[206:209], 0
	v_mfma_f32_16x16x32_bf16 v[60:63], v[152:155], v[186:189], v[60:63]
	v_mfma_f32_16x16x32_bf16 v[52:55], v[160:163], v[186:189], v[52:55]
	v_mfma_f32_16x16x32_bf16 v[44:47], v[152:155], v[194:197], v[44:47]
	v_mfma_f32_16x16x32_bf16 v[36:39], v[160:163], v[194:197], v[36:39]
	v_mfma_f32_16x16x32_bf16 v[28:31], v[152:155], v[202:205], v[28:31]
	v_mfma_f32_16x16x32_bf16 v[20:23], v[160:163], v[202:205], v[20:23]
	v_mfma_f32_16x16x32_bf16 v[12:15], v[152:155], v[210:213], v[12:15]
	v_mfma_f32_16x16x32_bf16 v[4:7], v[160:163], v[210:213], v[4:7]
	s_setprio 0
	s_setprio 1
	v_mfma_f32_16x16x32_bf16 v[56:59], v[164:167], v[182:185], 0
	v_mfma_f32_16x16x32_bf16 v[48:51], v[174:177], v[182:185], 0
	v_mfma_f32_16x16x32_bf16 v[40:43], v[164:167], v[190:193], 0
	v_mfma_f32_16x16x32_bf16 v[32:35], v[174:177], v[190:193], 0
	v_mfma_f32_16x16x32_bf16 v[24:27], v[164:167], v[198:201], 0
	v_mfma_f32_16x16x32_bf16 v[16:19], v[174:177], v[198:201], 0
	v_mfma_f32_16x16x32_bf16 v[8:11], v[164:167], v[206:209], 0
	v_mfma_f32_16x16x32_bf16 v[0:3], v[174:177], v[206:209], 0
	v_mfma_f32_16x16x32_bf16 v[56:59], v[170:173], v[186:189], v[56:59]
	v_mfma_f32_16x16x32_bf16 v[48:51], v[178:181], v[186:189], v[48:51]
	v_mfma_f32_16x16x32_bf16 v[40:43], v[170:173], v[194:197], v[40:43]
	v_mfma_f32_16x16x32_bf16 v[32:35], v[178:181], v[194:197], v[32:35]
	v_mfma_f32_16x16x32_bf16 v[24:27], v[170:173], v[202:205], v[24:27]
	v_mfma_f32_16x16x32_bf16 v[16:19], v[178:181], v[202:205], v[16:19]
	v_mfma_f32_16x16x32_bf16 v[8:11], v[170:173], v[210:213], v[8:11]
	v_mfma_f32_16x16x32_bf16 v[0:3], v[178:181], v[210:213], v[0:3]
	s_setprio 0
	s_barrier
	s_add_i32 s56, 0, 0x18000
	s_add_i32 s57, 0, 0x1c000
	v_add_u32_e32 v160, s56, v133
	v_add_u32_e32 v168, s57, v133
	ds_read_b128 v[148:151], v160
	ds_read_b128 v[152:155], v160 offset:1024
	ds_read_b128 v[156:159], v160 offset:2048
	ds_read_b128 v[160:163], v160 offset:3072
	ds_read_b128 v[164:167], v168
	ds_read_b128 v[170:173], v168 offset:1024
	ds_read_b128 v[174:177], v168 offset:2048
	ds_read_b128 v[178:181], v168 offset:3072
	s_add_u32 s34, s34, 0x2b0000
	s_addc_u32 s35, s35, 0
	s_mov_b32 m0, s39
	v_lshl_add_u64 v[222:223], s[34:35], 0, v[128:129]
	ds_read_b128 v[182:185], v147 offset:32768
	ds_read_b128 v[186:189], v147 offset:33792
	ds_read_b128 v[190:193], v147 offset:34816
	ds_read_b128 v[194:197], v147 offset:35840
	ds_read_b128 v[198:201], v147 offset:36864
	ds_read_b128 v[202:205], v147 offset:37888
	ds_read_b128 v[206:209], v147 offset:38912
	ds_read_b128 v[210:213], v147 offset:39936
	global_load_lds_dwordx4 v[222:223], off
	v_lshl_add_u64 v[222:223], s[34:35], 0, v[136:137]
	s_mov_b32 m0, s40
	s_nop 0
	global_load_lds_dwordx4 v[222:223], off
	s_waitcnt vmcnt(8)
	s_waitcnt lgkmcnt(0)
	s_barrier
	s_setprio 1
	s_waitcnt lgkmcnt(0)
	v_mfma_f32_16x16x32_bf16 v[124:127], v[148:151], v[182:185], v[124:127]
	v_mfma_f32_16x16x32_bf16 v[120:123], v[156:159], v[182:185], v[120:123]
	v_mfma_f32_16x16x32_bf16 v[108:111], v[148:151], v[190:193], v[108:111]
	v_mfma_f32_16x16x32_bf16 v[100:103], v[156:159], v[190:193], v[100:103]
	v_mfma_f32_16x16x32_bf16 v[92:95], v[148:151], v[198:201], v[92:95]
	v_mfma_f32_16x16x32_bf16 v[84:87], v[156:159], v[198:201], v[84:87]
	v_mfma_f32_16x16x32_bf16 v[76:79], v[148:151], v[206:209], v[76:79]
	v_mfma_f32_16x16x32_bf16 v[68:71], v[156:159], v[206:209], v[68:71]
	v_mfma_f32_16x16x32_bf16 v[124:127], v[152:155], v[186:189], v[124:127]
	v_mfma_f32_16x16x32_bf16 v[120:123], v[160:163], v[186:189], v[120:123]
	v_mfma_f32_16x16x32_bf16 v[108:111], v[152:155], v[194:197], v[108:111]
	v_mfma_f32_16x16x32_bf16 v[100:103], v[160:163], v[194:197], v[100:103]
	v_mfma_f32_16x16x32_bf16 v[92:95], v[152:155], v[202:205], v[92:95]
	v_mfma_f32_16x16x32_bf16 v[84:87], v[160:163], v[202:205], v[84:87]
	v_mfma_f32_16x16x32_bf16 v[76:79], v[152:155], v[210:213], v[76:79]
	v_mfma_f32_16x16x32_bf16 v[68:71], v[160:163], v[210:213], v[68:71]
	s_setprio 0
	s_setprio 1
	v_mfma_f32_16x16x32_bf16 v[116:119], v[164:167], v[182:185], v[116:119]
	v_mfma_f32_16x16x32_bf16 v[112:115], v[174:177], v[182:185], v[112:115]
	v_mfma_f32_16x16x32_bf16 v[104:107], v[164:167], v[190:193], v[104:107]
	v_mfma_f32_16x16x32_bf16 v[96:99], v[174:177], v[190:193], v[96:99]
	v_mfma_f32_16x16x32_bf16 v[88:91], v[164:167], v[198:201], v[88:91]
	v_mfma_f32_16x16x32_bf16 v[80:83], v[174:177], v[198:201], v[80:83]
	v_mfma_f32_16x16x32_bf16 v[72:75], v[164:167], v[206:209], v[72:75]
	v_mfma_f32_16x16x32_bf16 v[64:67], v[174:177], v[206:209], v[64:67]
	v_mfma_f32_16x16x32_bf16 v[116:119], v[170:173], v[186:189], v[116:119]
	v_mfma_f32_16x16x32_bf16 v[112:115], v[178:181], v[186:189], v[112:115]
	v_mfma_f32_16x16x32_bf16 v[104:107], v[170:173], v[194:197], v[104:107]
	v_mfma_f32_16x16x32_bf16 v[96:99], v[178:181], v[194:197], v[96:99]
	v_mfma_f32_16x16x32_bf16 v[88:91], v[170:173], v[202:205], v[88:91]
	v_mfma_f32_16x16x32_bf16 v[80:83], v[178:181], v[202:205], v[80:83]
	v_mfma_f32_16x16x32_bf16 v[72:75], v[170:173], v[210:213], v[72:75]
	v_mfma_f32_16x16x32_bf16 v[64:67], v[178:181], v[210:213], v[64:67]
	s_setprio 0
	s_barrier
	s_add_i32 s34, s56, s33
	v_lshl_add_u64 v[214:215], v[214:215], 0, s[6:7]
	s_mov_b32 m0, s34
	ds_read_b128 v[182:185], v147 offset:49152
	ds_read_b128 v[186:189], v147 offset:50176
	ds_read_b128 v[190:193], v147 offset:51200
	ds_read_b128 v[194:197], v147 offset:52224
	ds_read_b128 v[198:201], v147 offset:53248
	ds_read_b128 v[202:205], v147 offset:54272
	ds_read_b128 v[206:209], v147 offset:55296
	ds_read_b128 v[210:213], v147 offset:56320
	global_load_lds_dwordx4 v[214:215], off
	s_add_i32 m0, s34, 0x2000
	s_add_u32 s2, s2, 0x2b0080
	v_lshl_add_u64 v[214:215], v[216:217], 0, s[6:7]
	s_addc_u32 s3, s3, 0
	s_add_i32 s34, s57, s33
	global_load_lds_dwordx4 v[214:215], off
	v_lshl_add_u64 v[214:215], s[2:3], 0, v[134:135]
	s_mov_b32 m0, s34
	s_nop 0
	global_load_lds_dwordx4 v[214:215], off
	v_lshl_add_u64 v[214:215], s[2:3], 0, v[138:139]
	s_add_i32 m0, s34, 0x2000
	s_nop 0
	global_load_lds_dwordx4 v[214:215], off
	v_lshl_add_u64 v[214:215], v[218:219], 0, s[6:7]
	s_mov_b32 m0, s42
	s_nop 0
	global_load_lds_dwordx4 v[214:215], off
	v_lshl_add_u64 v[214:215], v[220:221], 0, s[6:7]
	s_mov_b32 m0, s43
	s_nop 0
	global_load_lds_dwordx4 v[214:215], off
	s_waitcnt vmcnt(8)
	s_waitcnt lgkmcnt(0)
	s_barrier
	s_setprio 1
	s_waitcnt lgkmcnt(0)
	v_mfma_f32_16x16x32_bf16 v[60:63], v[148:151], v[182:185], v[60:63]
	v_mfma_f32_16x16x32_bf16 v[52:55], v[156:159], v[182:185], v[52:55]
	v_mfma_f32_16x16x32_bf16 v[44:47], v[148:151], v[190:193], v[44:47]
	v_mfma_f32_16x16x32_bf16 v[36:39], v[156:159], v[190:193], v[36:39]
	v_mfma_f32_16x16x32_bf16 v[28:31], v[148:151], v[198:201], v[28:31]
	v_mfma_f32_16x16x32_bf16 v[20:23], v[156:159], v[198:201], v[20:23]
	v_mfma_f32_16x16x32_bf16 v[12:15], v[148:151], v[206:209], v[12:15]
	v_mfma_f32_16x16x32_bf16 v[4:7], v[156:159], v[206:209], v[4:7]
	v_mfma_f32_16x16x32_bf16 v[60:63], v[152:155], v[186:189], v[60:63]
	v_mfma_f32_16x16x32_bf16 v[52:55], v[160:163], v[186:189], v[52:55]
	v_mfma_f32_16x16x32_bf16 v[44:47], v[152:155], v[194:197], v[44:47]
	v_mfma_f32_16x16x32_bf16 v[36:39], v[160:163], v[194:197], v[36:39]
	v_mfma_f32_16x16x32_bf16 v[28:31], v[152:155], v[202:205], v[28:31]
	v_mfma_f32_16x16x32_bf16 v[20:23], v[160:163], v[202:205], v[20:23]
	v_mfma_f32_16x16x32_bf16 v[12:15], v[152:155], v[210:213], v[12:15]
	v_mfma_f32_16x16x32_bf16 v[4:7], v[160:163], v[210:213], v[4:7]
	s_setprio 0
	s_setprio 1
	v_mfma_f32_16x16x32_bf16 v[56:59], v[164:167], v[182:185], v[56:59]
	v_mfma_f32_16x16x32_bf16 v[48:51], v[174:177], v[182:185], v[48:51]
	v_mfma_f32_16x16x32_bf16 v[40:43], v[164:167], v[190:193], v[40:43]
	v_mfma_f32_16x16x32_bf16 v[32:35], v[174:177], v[190:193], v[32:35]
	v_mfma_f32_16x16x32_bf16 v[24:27], v[164:167], v[198:201], v[24:27]
	v_mfma_f32_16x16x32_bf16 v[16:19], v[174:177], v[198:201], v[16:19]
	v_mfma_f32_16x16x32_bf16 v[8:11], v[164:167], v[206:209], v[8:11]
	v_mfma_f32_16x16x32_bf16 v[0:3], v[174:177], v[206:209], v[0:3]
	v_mfma_f32_16x16x32_bf16 v[56:59], v[170:173], v[186:189], v[56:59]
	v_mfma_f32_16x16x32_bf16 v[48:51], v[178:181], v[186:189], v[48:51]
	v_mfma_f32_16x16x32_bf16 v[40:43], v[170:173], v[194:197], v[40:43]
	v_mfma_f32_16x16x32_bf16 v[32:35], v[178:181], v[194:197], v[32:35]
	v_mfma_f32_16x16x32_bf16 v[24:27], v[170:173], v[202:205], v[24:27]
	v_mfma_f32_16x16x32_bf16 v[16:19], v[178:181], v[202:205], v[16:19]
	v_mfma_f32_16x16x32_bf16 v[8:11], v[170:173], v[210:213], v[8:11]
	v_mfma_f32_16x16x32_bf16 v[0:3], v[178:181], v[210:213], v[0:3]
	s_setprio 0
	s_barrier
	s_add_u32 s30, s30, 0x100
	s_addc_u32 s31, s31, 0
	s_add_u32 s28, s28, 0x100
	s_addc_u32 s52, s52, 0
	s_cmp_ge_i32 s53, s29
	s_mov_b32 s2, s53
	s_cbranch_scc1 .Lkpeel_exit_6

.Lkpeel_exit_6:
	s_and_b64 vcc, exec, s[12:13]
	s_cbranch_vccz .LBB0_1131
